# plus P7 EpiGlu hb loads hoisted (8 per tile) and P12 head epilogue ssq loads hoisted
# speedup vs baseline: 1.0048x; 1.0048x over previous
.LBB0_957:
	v_lshl_add_u32 v148, s24, 8, v151
	v_ashrrev_i32_e32 v149, 31, v148
	v_lshl_or_b32 v146, s26, 7, v153
	v_lshlrev_b64 v[158:159], 11, v[148:149]
	v_ashrrev_i32_e32 v147, 31, v146
	v_lshl_add_u64 v[158:159], s[92:93], 0, v[158:159]
	v_lshl_add_u64 v[162:163], v[146:147], 1, v[158:159]
	global_load_dwordx4 v[172:175], v[162:163], off
	v_or_b32_e32 v214, 16, v148
	v_ashrrev_i32_e32 v215, 31, v214
	v_lshlrev_b64 v[216:217], 11, v[214:215]
	v_lshl_add_u64 v[216:217], s[92:93], 0, v[216:217]
	v_lshl_add_u64 v[218:219], v[146:147], 1, v[216:217]
	global_load_dwordx4 v[182:185], v[218:219], off
	v_or_b32_e32 v220, 32, v148
	v_ashrrev_i32_e32 v221, 31, v220
	v_lshlrev_b64 v[246:247], 11, v[220:221]
	v_lshl_add_u64 v[246:247], s[92:93], 0, v[246:247]
	v_lshl_add_u64 v[252:253], v[146:147], 1, v[246:247]
	global_load_dwordx4 v[186:189], v[252:253], off
	v_or_b32_e32 v254, 48, v148
	v_ashrrev_i32_e32 v255, 31, v254
	v_lshlrev_b64 v[214:215], 11, v[254:255]
	v_lshl_add_u64 v[214:215], s[92:93], 0, v[214:215]
	v_lshl_add_u64 v[216:217], v[146:147], 1, v[214:215]
	global_load_dwordx4 v[190:193], v[216:217], off
	v_add_u32_e32 v218, 0x80, v148
	v_ashrrev_i32_e32 v219, 31, v218
	v_lshlrev_b64 v[220:221], 11, v[218:219]
	v_lshl_add_u64 v[220:221], s[92:93], 0, v[220:221]
	v_lshl_add_u64 v[246:247], v[146:147], 1, v[220:221]
	global_load_dwordx4 v[194:197], v[246:247], off
	v_add_u32_e32 v252, 0x90, v148
	v_ashrrev_i32_e32 v253, 31, v252
	v_lshlrev_b64 v[254:255], 11, v[252:253]
	v_lshl_add_u64 v[254:255], s[92:93], 0, v[254:255]
	v_lshl_add_u64 v[214:215], v[146:147], 1, v[254:255]
	global_load_dwordx4 v[198:201], v[214:215], off
	v_add_u32_e32 v216, 0xa0, v148
	v_ashrrev_i32_e32 v217, 31, v216
	v_lshlrev_b64 v[218:219], 11, v[216:217]
	v_lshl_add_u64 v[218:219], s[92:93], 0, v[218:219]
	v_lshl_add_u64 v[220:221], v[146:147], 1, v[218:219]
	global_load_dwordx4 v[202:205], v[220:221], off
	v_add_u32_e32 v246, 0xb0, v148
	v_ashrrev_i32_e32 v247, 31, v246
	v_lshlrev_b64 v[252:253], 11, v[246:247]
	v_lshl_add_u64 v[252:253], s[92:93], 0, v[252:253]
	v_lshl_add_u64 v[254:255], v[146:147], 1, v[252:253]
	global_load_dwordx4 v[206:209], v[254:255], off
	s_nop 0
	v_mul_f32_e32 v126, 0xbfb8aa3b, v126
	v_mul_f32_e32 v127, 0xbfb8aa3b, v127
	v_mul_f32_e32 v128, 0xbfb8aa3b, v128
	v_mul_f32_e32 v129, 0xbfb8aa3b, v129
	v_mul_f32_e32 v122, 0xbfb8aa3b, v122
	v_mul_f32_e32 v123, 0xbfb8aa3b, v123
	v_mul_f32_e32 v124, 0xbfb8aa3b, v124
	v_mul_f32_e32 v125, 0xbfb8aa3b, v125
	v_exp_f32_e32 v126, v126
	v_exp_f32_e32 v127, v127
	v_exp_f32_e32 v128, v128
	v_exp_f32_e32 v129, v129
	v_exp_f32_e32 v166, v122
	v_exp_f32_e32 v123, v123
	v_exp_f32_e32 v124, v124
	v_exp_f32_e32 v125, v125
	v_and_b32_e32 v165, 64, v157
	v_xor_b32_e32 v164, 16, v157
	v_add_u32_e32 v170, 64, v165
	v_cmp_lt_i32_e32 vcc, v164, v170
	v_add_f32_e32 v126, 1.0, v126
	v_add_f32_e32 v127, 1.0, v127
	v_cndmask_b32_e32 v122, v157, v164, vcc
	v_add_f32_e32 v128, 1.0, v128
	v_add_f32_e32 v129, 1.0, v129
	v_add_f32_e32 v164, 1.0, v166
	v_add_f32_e32 v123, 1.0, v123
	v_add_f32_e32 v165, 1.0, v124
	v_add_f32_e32 v166, 1.0, v125
	v_rcp_f32_e32 v124, v126
	v_rcp_f32_e32 v125, v127
	v_rcp_f32_e32 v126, v128
	v_rcp_f32_e32 v127, v129
	v_rcp_f32_e32 v128, v164
	v_rcp_f32_e32 v129, v123
	v_rcp_f32_e32 v164, v165
	v_rcp_f32_e32 v165, v166
	v_lshlrev_b32_e32 v122, 2, v122
	s_waitcnt vmcnt(7)
	v_lshlrev_b32_e32 v166, 16, v172
	v_and_b32_e32 v167, 0xffff0000, v172
	v_lshlrev_b32_e32 v158, 16, v173
	v_and_b32_e32 v159, 0xffff0000, v173
	v_lshlrev_b32_e32 v168, 16, v174
	v_and_b32_e32 v169, 0xffff0000, v174
	v_lshlrev_b32_e32 v160, 16, v175
	v_and_b32_e32 v161, 0xffff0000, v175
	v_pk_fma_f32 v[120:121], v[120:121], v[126:127], v[158:159]
	v_pk_fma_f32 v[118:119], v[118:119], v[124:125], v[166:167]
	v_pk_fma_f32 v[124:125], v[116:117], v[164:165], v[160:161]
	v_pk_fma_f32 v[126:127], v[114:115], v[128:129], v[168:169]
	v_pk_mul_f32 v[114:115], v[120:121], v[120:121]
	v_pk_mul_f32 v[116:117], v[118:119], v[118:119]
	v_pk_mul_f32 v[128:129], v[124:125], v[124:125]
	v_pk_mul_f32 v[158:159], v[126:127], v[126:127]
	v_add_f32_e32 v116, v116, v117
	v_add_f32_e32 v114, v114, v115
	v_add_f32_e32 v115, v158, v159
	v_add_f32_e32 v117, v128, v129
	v_add_f32_e32 v114, v116, v114
	v_add_f32_e32 v115, v115, v117
	v_add_f32_e32 v114, v114, v115
	ds_bpermute_b32 v115, v122, v114
	v_xor_b32_e32 v116, 32, v157
	v_cmp_lt_i32_e32 vcc, v116, v170
	v_cvt_pk_bf16_f32 v118, v118, v119
	v_cvt_pk_bf16_f32 v119, v120, v121
	s_waitcnt lgkmcnt(0)
	v_add_f32_e32 v114, v114, v115
	v_cvt_pk_bf16_f32 v120, v126, v127
	v_cvt_pk_bf16_f32 v121, v124, v125
	v_cndmask_b32_e32 v116, v157, v116, vcc
	v_lshlrev_b32_e32 v116, 2, v116
	ds_bpermute_b32 v115, v116, v114
	global_store_dwordx4 v[162:163], v[118:121], off
	s_and_saveexec_b64 s[24:25], s[2:3]
	s_cbranch_execz .LBB0_959
	s_waitcnt lgkmcnt(0)
	v_add_f32_e32 v117, v114, v115
	v_lshl_add_u64 v[114:115], v[148:149], 2, s[10:11]
	global_atomic_add_f32 v[114:115], v117, off
.LBB0_959:
	s_or_b64 exec, exec, s[24:25]
	v_or_b32_e32 v114, 16, v148
	s_waitcnt lgkmcnt(0)
	v_ashrrev_i32_e32 v115, 31, v114
	v_lshlrev_b64 v[118:119], 11, v[114:115]
	v_lshl_add_u64 v[118:119], s[92:93], 0, v[118:119]
	v_lshl_add_u64 v[124:125], v[146:147], 1, v[118:119]
	s_nop 0
	v_mul_f32_e32 v110, 0xbfb8aa3b, v110
	v_mul_f32_e32 v111, 0xbfb8aa3b, v111
	v_mul_f32_e32 v112, 0xbfb8aa3b, v112
	v_mul_f32_e32 v113, 0xbfb8aa3b, v113
	v_mul_f32_e32 v106, 0xbfb8aa3b, v106
	v_mul_f32_e32 v107, 0xbfb8aa3b, v107
	v_mul_f32_e32 v108, 0xbfb8aa3b, v108
	v_mul_f32_e32 v109, 0xbfb8aa3b, v109
	v_exp_f32_e32 v110, v110
	v_exp_f32_e32 v111, v111
	v_exp_f32_e32 v112, v112
	v_exp_f32_e32 v113, v113
	v_exp_f32_e32 v106, v106
	v_exp_f32_e32 v107, v107
	v_exp_f32_e32 v108, v108
	v_exp_f32_e32 v109, v109
	v_add_f32_e32 v110, 1.0, v110
	v_add_f32_e32 v111, 1.0, v111
	v_add_f32_e32 v112, 1.0, v112
	v_add_f32_e32 v113, 1.0, v113
	v_add_f32_e32 v117, 1.0, v106
	v_add_f32_e32 v123, 1.0, v107
	v_add_f32_e32 v126, 1.0, v108
	v_add_f32_e32 v127, 1.0, v109
	v_rcp_f32_e32 v106, v110
	v_rcp_f32_e32 v107, v111
	v_rcp_f32_e32 v108, v112
	v_rcp_f32_e32 v109, v113
	v_rcp_f32_e32 v110, v117
	v_rcp_f32_e32 v111, v123
	v_rcp_f32_e32 v112, v126
	v_rcp_f32_e32 v113, v127
	s_waitcnt vmcnt(7)
	v_lshlrev_b32_e32 v126, 16, v182
	v_and_b32_e32 v127, 0xffff0000, v182
	v_lshlrev_b32_e32 v118, 16, v183
	v_and_b32_e32 v119, 0xffff0000, v183
	v_lshlrev_b32_e32 v128, 16, v184
	v_and_b32_e32 v129, 0xffff0000, v184
	v_lshlrev_b32_e32 v120, 16, v185
	v_and_b32_e32 v121, 0xffff0000, v185
	v_pk_fma_f32 v[104:105], v[104:105], v[108:109], v[118:119]
	v_pk_fma_f32 v[102:103], v[102:103], v[106:107], v[126:127]
	v_pk_fma_f32 v[106:107], v[100:101], v[112:113], v[120:121]
	v_pk_fma_f32 v[108:109], v[98:99], v[110:111], v[128:129]
	v_pk_mul_f32 v[98:99], v[104:105], v[104:105]
	v_pk_mul_f32 v[100:101], v[102:103], v[102:103]
	v_pk_mul_f32 v[110:111], v[106:107], v[106:107]
	v_pk_mul_f32 v[112:113], v[108:109], v[108:109]
	v_add_f32_e32 v100, v100, v101
	v_add_f32_e32 v98, v98, v99
	v_add_f32_e32 v99, v112, v113
	v_add_f32_e32 v101, v110, v111
	v_add_f32_e32 v98, v100, v98
	v_add_f32_e32 v99, v99, v101
	v_add_f32_e32 v98, v98, v99
	ds_bpermute_b32 v99, v122, v98
	v_cvt_pk_bf16_f32 v100, v102, v103
	v_cvt_pk_bf16_f32 v101, v104, v105
	v_cvt_pk_bf16_f32 v102, v108, v109
	v_cvt_pk_bf16_f32 v103, v106, v107
	s_waitcnt lgkmcnt(0)
	v_add_f32_e32 v98, v98, v99
	ds_bpermute_b32 v99, v116, v98
	global_store_dwordx4 v[124:125], v[100:103], off
	s_and_saveexec_b64 s[24:25], s[2:3]
	s_cbranch_execz .LBB0_961
	s_waitcnt lgkmcnt(0)
	v_add_f32_e32 v100, v98, v99
	v_lshl_add_u64 v[98:99], v[114:115], 2, s[10:11]
	global_atomic_add_f32 v[98:99], v100, off
.LBB0_961:
	s_or_b64 exec, exec, s[24:25]
	v_or_b32_e32 v98, 32, v148
	s_waitcnt lgkmcnt(0)
	v_ashrrev_i32_e32 v99, 31, v98
	v_lshlrev_b64 v[100:101], 11, v[98:99]
	v_lshl_add_u64 v[100:101], s[92:93], 0, v[100:101]
	v_lshl_add_u64 v[104:105], v[146:147], 1, v[100:101]
	s_nop 0
	v_mul_f32_e32 v94, 0xbfb8aa3b, v94
	v_mul_f32_e32 v95, 0xbfb8aa3b, v95
	v_mul_f32_e32 v96, 0xbfb8aa3b, v96
	v_mul_f32_e32 v97, 0xbfb8aa3b, v97
	v_mul_f32_e32 v90, 0xbfb8aa3b, v90
	v_mul_f32_e32 v91, 0xbfb8aa3b, v91
	v_mul_f32_e32 v92, 0xbfb8aa3b, v92
	v_mul_f32_e32 v93, 0xbfb8aa3b, v93
	v_exp_f32_e32 v94, v94
	v_exp_f32_e32 v95, v95
	v_exp_f32_e32 v96, v96
	v_exp_f32_e32 v97, v97
	v_exp_f32_e32 v90, v90
	v_exp_f32_e32 v91, v91
	v_exp_f32_e32 v92, v92
	v_exp_f32_e32 v93, v93
	v_add_f32_e32 v94, 1.0, v94
	v_add_f32_e32 v95, 1.0, v95
	v_add_f32_e32 v96, 1.0, v96
	v_add_f32_e32 v97, 1.0, v97
	v_add_f32_e32 v106, 1.0, v90
	v_add_f32_e32 v107, 1.0, v91
	v_add_f32_e32 v108, 1.0, v92
	v_add_f32_e32 v109, 1.0, v93
	v_rcp_f32_e32 v90, v94
	v_rcp_f32_e32 v91, v95
	v_rcp_f32_e32 v92, v96
	v_rcp_f32_e32 v93, v97
	v_rcp_f32_e32 v94, v106
	v_rcp_f32_e32 v95, v107
	v_rcp_f32_e32 v96, v108
	v_rcp_f32_e32 v97, v109
	s_waitcnt vmcnt(7)
	v_lshlrev_b32_e32 v106, 16, v186
	v_and_b32_e32 v107, 0xffff0000, v186
	v_lshlrev_b32_e32 v100, 16, v187
	v_and_b32_e32 v101, 0xffff0000, v187
	v_lshlrev_b32_e32 v108, 16, v188
	v_and_b32_e32 v109, 0xffff0000, v188
	v_lshlrev_b32_e32 v102, 16, v189
	v_and_b32_e32 v103, 0xffff0000, v189
	v_pk_fma_f32 v[88:89], v[88:89], v[92:93], v[100:101]
	v_pk_fma_f32 v[86:87], v[86:87], v[90:91], v[106:107]
	v_pk_fma_f32 v[90:91], v[84:85], v[96:97], v[102:103]
	v_pk_fma_f32 v[92:93], v[82:83], v[94:95], v[108:109]
	v_pk_mul_f32 v[82:83], v[88:89], v[88:89]
	v_pk_mul_f32 v[84:85], v[86:87], v[86:87]
	v_pk_mul_f32 v[94:95], v[90:91], v[90:91]
	v_pk_mul_f32 v[96:97], v[92:93], v[92:93]
	v_add_f32_e32 v84, v84, v85
	v_add_f32_e32 v82, v82, v83
	v_add_f32_e32 v83, v96, v97
	v_add_f32_e32 v85, v94, v95
	v_add_f32_e32 v82, v84, v82
	v_add_f32_e32 v83, v83, v85
	v_add_f32_e32 v82, v82, v83
	ds_bpermute_b32 v83, v122, v82
	v_cvt_pk_bf16_f32 v84, v86, v87
	v_cvt_pk_bf16_f32 v85, v88, v89
	v_cvt_pk_bf16_f32 v86, v92, v93
	v_cvt_pk_bf16_f32 v87, v90, v91
	s_waitcnt lgkmcnt(0)
	v_add_f32_e32 v82, v82, v83
	ds_bpermute_b32 v83, v116, v82
	global_store_dwordx4 v[104:105], v[84:87], off
	s_and_saveexec_b64 s[24:25], s[2:3]
	s_cbranch_execz .LBB0_963
	s_waitcnt lgkmcnt(0)
	v_add_f32_e32 v84, v82, v83
	v_lshl_add_u64 v[82:83], v[98:99], 2, s[10:11]
	global_atomic_add_f32 v[82:83], v84, off
.LBB0_963:
	s_or_b64 exec, exec, s[24:25]
	v_or_b32_e32 v82, 48, v148
	s_waitcnt lgkmcnt(0)
	v_ashrrev_i32_e32 v83, 31, v82
	v_lshlrev_b64 v[84:85], 11, v[82:83]
	v_lshl_add_u64 v[84:85], s[92:93], 0, v[84:85]
	v_lshl_add_u64 v[88:89], v[146:147], 1, v[84:85]
	s_nop 0
	v_mul_f32_e32 v78, 0xbfb8aa3b, v78
	v_mul_f32_e32 v79, 0xbfb8aa3b, v79
	v_mul_f32_e32 v80, 0xbfb8aa3b, v80
	v_mul_f32_e32 v81, 0xbfb8aa3b, v81
	v_mul_f32_e32 v74, 0xbfb8aa3b, v74
	v_mul_f32_e32 v75, 0xbfb8aa3b, v75
	v_mul_f32_e32 v76, 0xbfb8aa3b, v76
	v_mul_f32_e32 v77, 0xbfb8aa3b, v77
	v_exp_f32_e32 v78, v78
	v_exp_f32_e32 v79, v79
	v_exp_f32_e32 v80, v80
	v_exp_f32_e32 v81, v81
	v_exp_f32_e32 v74, v74
	v_exp_f32_e32 v75, v75
	v_exp_f32_e32 v76, v76
	v_exp_f32_e32 v77, v77
	v_add_f32_e32 v78, 1.0, v78
	v_add_f32_e32 v79, 1.0, v79
	v_add_f32_e32 v80, 1.0, v80
	v_add_f32_e32 v81, 1.0, v81
	v_add_f32_e32 v90, 1.0, v74
	v_add_f32_e32 v91, 1.0, v75
	v_add_f32_e32 v92, 1.0, v76
	v_add_f32_e32 v93, 1.0, v77
	v_rcp_f32_e32 v74, v78
	v_rcp_f32_e32 v75, v79
	v_rcp_f32_e32 v76, v80
	v_rcp_f32_e32 v77, v81
	v_rcp_f32_e32 v78, v90
	v_rcp_f32_e32 v79, v91
	v_rcp_f32_e32 v80, v92
	v_rcp_f32_e32 v81, v93
	s_waitcnt vmcnt(7)
	v_lshlrev_b32_e32 v90, 16, v190
	v_and_b32_e32 v91, 0xffff0000, v190
	v_lshlrev_b32_e32 v84, 16, v191
	v_and_b32_e32 v85, 0xffff0000, v191
	v_lshlrev_b32_e32 v92, 16, v192
	v_and_b32_e32 v93, 0xffff0000, v192
	v_lshlrev_b32_e32 v86, 16, v193
	v_and_b32_e32 v87, 0xffff0000, v193
	v_pk_fma_f32 v[72:73], v[72:73], v[76:77], v[84:85]
	v_pk_fma_f32 v[70:71], v[70:71], v[74:75], v[90:91]
	v_pk_fma_f32 v[74:75], v[68:69], v[80:81], v[86:87]
	v_pk_fma_f32 v[76:77], v[66:67], v[78:79], v[92:93]
	v_pk_mul_f32 v[66:67], v[72:73], v[72:73]
	v_pk_mul_f32 v[68:69], v[70:71], v[70:71]
	v_pk_mul_f32 v[78:79], v[74:75], v[74:75]
	v_pk_mul_f32 v[80:81], v[76:77], v[76:77]
	v_add_f32_e32 v68, v68, v69
	v_add_f32_e32 v66, v66, v67
	v_add_f32_e32 v67, v80, v81
	v_add_f32_e32 v69, v78, v79
	v_add_f32_e32 v66, v68, v66
	v_add_f32_e32 v67, v67, v69
	v_add_f32_e32 v66, v66, v67
	ds_bpermute_b32 v67, v122, v66
	v_cvt_pk_bf16_f32 v68, v70, v71
	v_cvt_pk_bf16_f32 v69, v72, v73
	v_cvt_pk_bf16_f32 v70, v76, v77
	v_cvt_pk_bf16_f32 v71, v74, v75
	s_waitcnt lgkmcnt(0)
	v_add_f32_e32 v66, v66, v67
	ds_bpermute_b32 v67, v116, v66
	global_store_dwordx4 v[88:89], v[68:71], off
	s_and_saveexec_b64 s[24:25], s[2:3]
	s_cbranch_execz .LBB0_965
	s_waitcnt lgkmcnt(0)
	v_add_f32_e32 v68, v66, v67
	v_lshl_add_u64 v[66:67], v[82:83], 2, s[10:11]
	global_atomic_add_f32 v[66:67], v68, off
.LBB0_965:
	s_or_b64 exec, exec, s[24:25]
	v_add_u32_e32 v66, 0x80, v148
	s_waitcnt lgkmcnt(0)
	v_ashrrev_i32_e32 v67, 31, v66
	v_lshlrev_b64 v[68:69], 11, v[66:67]
	v_lshl_add_u64 v[68:69], s[92:93], 0, v[68:69]
	v_lshl_add_u64 v[72:73], v[146:147], 1, v[68:69]
	s_nop 0
	v_mul_f32_e32 v62, 0xbfb8aa3b, v62
	v_mul_f32_e32 v63, 0xbfb8aa3b, v63
	v_mul_f32_e32 v64, 0xbfb8aa3b, v64
	v_mul_f32_e32 v65, 0xbfb8aa3b, v65
	v_mul_f32_e32 v58, 0xbfb8aa3b, v58
	v_mul_f32_e32 v59, 0xbfb8aa3b, v59
	v_mul_f32_e32 v60, 0xbfb8aa3b, v60
	v_mul_f32_e32 v61, 0xbfb8aa3b, v61
	v_exp_f32_e32 v62, v62
	v_exp_f32_e32 v63, v63
	v_exp_f32_e32 v64, v64
	v_exp_f32_e32 v65, v65
	v_exp_f32_e32 v58, v58
	v_exp_f32_e32 v59, v59
	v_exp_f32_e32 v60, v60
	v_exp_f32_e32 v61, v61
	v_add_f32_e32 v62, 1.0, v62
	v_add_f32_e32 v63, 1.0, v63
	v_add_f32_e32 v64, 1.0, v64
	v_add_f32_e32 v65, 1.0, v65
	v_add_f32_e32 v74, 1.0, v58
	v_add_f32_e32 v75, 1.0, v59
	v_add_f32_e32 v76, 1.0, v60
	v_add_f32_e32 v77, 1.0, v61
	v_rcp_f32_e32 v58, v62
	v_rcp_f32_e32 v59, v63
	v_rcp_f32_e32 v60, v64
	v_rcp_f32_e32 v61, v65
	v_rcp_f32_e32 v62, v74
	v_rcp_f32_e32 v63, v75
	v_rcp_f32_e32 v64, v76
	v_rcp_f32_e32 v65, v77
	s_waitcnt vmcnt(7)
	v_lshlrev_b32_e32 v74, 16, v194
	v_and_b32_e32 v75, 0xffff0000, v194
	v_lshlrev_b32_e32 v68, 16, v195
	v_and_b32_e32 v69, 0xffff0000, v195
	v_lshlrev_b32_e32 v76, 16, v196
	v_and_b32_e32 v77, 0xffff0000, v196
	v_lshlrev_b32_e32 v70, 16, v197
	v_and_b32_e32 v71, 0xffff0000, v197
	v_pk_fma_f32 v[56:57], v[56:57], v[60:61], v[68:69]
	v_pk_fma_f32 v[54:55], v[54:55], v[58:59], v[74:75]
	v_pk_fma_f32 v[58:59], v[52:53], v[64:65], v[70:71]
	v_pk_fma_f32 v[60:61], v[50:51], v[62:63], v[76:77]
	v_pk_mul_f32 v[50:51], v[56:57], v[56:57]
	v_pk_mul_f32 v[52:53], v[54:55], v[54:55]
	v_pk_mul_f32 v[62:63], v[58:59], v[58:59]
	v_pk_mul_f32 v[64:65], v[60:61], v[60:61]
	v_add_f32_e32 v52, v52, v53
	v_add_f32_e32 v50, v50, v51
	v_add_f32_e32 v51, v64, v65
	v_add_f32_e32 v53, v62, v63
	v_add_f32_e32 v50, v52, v50
	v_add_f32_e32 v51, v51, v53
	v_add_f32_e32 v50, v50, v51
	ds_bpermute_b32 v51, v122, v50
	v_cvt_pk_bf16_f32 v52, v54, v55
	v_cvt_pk_bf16_f32 v53, v56, v57
	v_cvt_pk_bf16_f32 v54, v60, v61
	v_cvt_pk_bf16_f32 v55, v58, v59
	s_waitcnt lgkmcnt(0)
	v_add_f32_e32 v50, v50, v51
	ds_bpermute_b32 v51, v116, v50
	global_store_dwordx4 v[72:73], v[52:55], off
	s_and_saveexec_b64 s[24:25], s[2:3]
	s_cbranch_execz .LBB0_967
	s_waitcnt lgkmcnt(0)
	v_add_f32_e32 v52, v50, v51
	v_lshl_add_u64 v[50:51], v[66:67], 2, s[10:11]
	global_atomic_add_f32 v[50:51], v52, off
.LBB0_967:
	s_or_b64 exec, exec, s[24:25]
	v_add_u32_e32 v50, 0x90, v148
	s_waitcnt lgkmcnt(0)
	v_ashrrev_i32_e32 v51, 31, v50
	v_lshlrev_b64 v[52:53], 11, v[50:51]
	v_lshl_add_u64 v[52:53], s[92:93], 0, v[52:53]
	v_lshl_add_u64 v[56:57], v[146:147], 1, v[52:53]
	s_nop 0
	v_mul_f32_e32 v46, 0xbfb8aa3b, v46
	v_mul_f32_e32 v47, 0xbfb8aa3b, v47
	v_mul_f32_e32 v48, 0xbfb8aa3b, v48
	v_mul_f32_e32 v49, 0xbfb8aa3b, v49
	v_mul_f32_e32 v42, 0xbfb8aa3b, v42
	v_mul_f32_e32 v43, 0xbfb8aa3b, v43
	v_mul_f32_e32 v44, 0xbfb8aa3b, v44
	v_mul_f32_e32 v45, 0xbfb8aa3b, v45
	v_exp_f32_e32 v46, v46
	v_exp_f32_e32 v47, v47
	v_exp_f32_e32 v48, v48
	v_exp_f32_e32 v49, v49
	v_exp_f32_e32 v42, v42
	v_exp_f32_e32 v43, v43
	v_exp_f32_e32 v44, v44
	v_exp_f32_e32 v45, v45
	v_add_f32_e32 v46, 1.0, v46
	v_add_f32_e32 v47, 1.0, v47
	v_add_f32_e32 v48, 1.0, v48
	v_add_f32_e32 v49, 1.0, v49
	v_add_f32_e32 v58, 1.0, v42
	v_add_f32_e32 v59, 1.0, v43
	v_add_f32_e32 v60, 1.0, v44
	v_add_f32_e32 v61, 1.0, v45
	v_rcp_f32_e32 v42, v46
	v_rcp_f32_e32 v43, v47
	v_rcp_f32_e32 v44, v48
	v_rcp_f32_e32 v45, v49
	v_rcp_f32_e32 v46, v58
	v_rcp_f32_e32 v47, v59
	v_rcp_f32_e32 v48, v60
	v_rcp_f32_e32 v49, v61
	s_waitcnt vmcnt(7)
	v_lshlrev_b32_e32 v58, 16, v198
	v_and_b32_e32 v59, 0xffff0000, v198
	v_lshlrev_b32_e32 v52, 16, v199
	v_and_b32_e32 v53, 0xffff0000, v199
	v_lshlrev_b32_e32 v60, 16, v200
	v_and_b32_e32 v61, 0xffff0000, v200
	v_lshlrev_b32_e32 v54, 16, v201
	v_and_b32_e32 v55, 0xffff0000, v201
	v_pk_fma_f32 v[40:41], v[40:41], v[44:45], v[52:53]
	v_pk_fma_f32 v[38:39], v[38:39], v[42:43], v[58:59]
	v_pk_fma_f32 v[42:43], v[36:37], v[48:49], v[54:55]
	v_pk_fma_f32 v[44:45], v[34:35], v[46:47], v[60:61]
	v_pk_mul_f32 v[34:35], v[40:41], v[40:41]
	v_pk_mul_f32 v[36:37], v[38:39], v[38:39]
	v_pk_mul_f32 v[46:47], v[42:43], v[42:43]
	v_pk_mul_f32 v[48:49], v[44:45], v[44:45]
	v_add_f32_e32 v36, v36, v37
	v_add_f32_e32 v34, v34, v35
	v_add_f32_e32 v35, v48, v49
	v_add_f32_e32 v37, v46, v47
	v_add_f32_e32 v34, v36, v34
	v_add_f32_e32 v35, v35, v37
	v_add_f32_e32 v34, v34, v35
	ds_bpermute_b32 v35, v122, v34
	v_cvt_pk_bf16_f32 v36, v38, v39
	v_cvt_pk_bf16_f32 v37, v40, v41
	v_cvt_pk_bf16_f32 v38, v44, v45
	v_cvt_pk_bf16_f32 v39, v42, v43
	s_waitcnt lgkmcnt(0)
	v_add_f32_e32 v34, v34, v35
	ds_bpermute_b32 v35, v116, v34
	global_store_dwordx4 v[56:57], v[36:39], off
	s_and_saveexec_b64 s[24:25], s[2:3]
	s_cbranch_execz .LBB0_969
	s_waitcnt lgkmcnt(0)
	v_add_f32_e32 v36, v34, v35
	v_lshl_add_u64 v[34:35], v[50:51], 2, s[10:11]
	global_atomic_add_f32 v[34:35], v36, off
.LBB0_969:
	s_or_b64 exec, exec, s[24:25]
	v_add_u32_e32 v34, 0xa0, v148
	s_waitcnt lgkmcnt(0)
	v_ashrrev_i32_e32 v35, 31, v34
	v_lshlrev_b64 v[36:37], 11, v[34:35]
	v_lshl_add_u64 v[36:37], s[92:93], 0, v[36:37]
	v_lshl_add_u64 v[40:41], v[146:147], 1, v[36:37]
	s_nop 0
	v_mul_f32_e32 v30, 0xbfb8aa3b, v30
	v_mul_f32_e32 v31, 0xbfb8aa3b, v31
	v_mul_f32_e32 v32, 0xbfb8aa3b, v32
	v_mul_f32_e32 v33, 0xbfb8aa3b, v33
	v_mul_f32_e32 v26, 0xbfb8aa3b, v26
	v_mul_f32_e32 v27, 0xbfb8aa3b, v27
	v_mul_f32_e32 v28, 0xbfb8aa3b, v28
	v_mul_f32_e32 v29, 0xbfb8aa3b, v29
	v_exp_f32_e32 v30, v30
	v_exp_f32_e32 v31, v31
	v_exp_f32_e32 v32, v32
	v_exp_f32_e32 v33, v33
	v_exp_f32_e32 v26, v26
	v_exp_f32_e32 v27, v27
	v_exp_f32_e32 v28, v28
	v_exp_f32_e32 v29, v29
	v_add_f32_e32 v30, 1.0, v30
	v_add_f32_e32 v31, 1.0, v31
	v_add_f32_e32 v32, 1.0, v32
	v_add_f32_e32 v33, 1.0, v33
	v_add_f32_e32 v42, 1.0, v26
	v_add_f32_e32 v43, 1.0, v27
	v_add_f32_e32 v44, 1.0, v28
	v_add_f32_e32 v45, 1.0, v29
	v_rcp_f32_e32 v26, v30
	v_rcp_f32_e32 v27, v31
	v_rcp_f32_e32 v28, v32
	v_rcp_f32_e32 v29, v33
	v_rcp_f32_e32 v30, v42
	v_rcp_f32_e32 v31, v43
	v_rcp_f32_e32 v32, v44
	v_rcp_f32_e32 v33, v45
	s_waitcnt vmcnt(7)
	v_lshlrev_b32_e32 v42, 16, v202
	v_and_b32_e32 v43, 0xffff0000, v202
	v_lshlrev_b32_e32 v36, 16, v203
	v_and_b32_e32 v37, 0xffff0000, v203
	v_lshlrev_b32_e32 v44, 16, v204
	v_and_b32_e32 v45, 0xffff0000, v204
	v_lshlrev_b32_e32 v38, 16, v205
	v_and_b32_e32 v39, 0xffff0000, v205
	v_pk_fma_f32 v[24:25], v[24:25], v[28:29], v[36:37]
	v_pk_fma_f32 v[22:23], v[22:23], v[26:27], v[42:43]
	v_pk_fma_f32 v[26:27], v[20:21], v[32:33], v[38:39]
	v_pk_fma_f32 v[28:29], v[18:19], v[30:31], v[44:45]
	v_pk_mul_f32 v[18:19], v[24:25], v[24:25]
	v_pk_mul_f32 v[20:21], v[22:23], v[22:23]
	v_pk_mul_f32 v[30:31], v[26:27], v[26:27]
	v_pk_mul_f32 v[32:33], v[28:29], v[28:29]
	v_add_f32_e32 v20, v20, v21
	v_add_f32_e32 v18, v18, v19
	v_add_f32_e32 v19, v32, v33
	v_add_f32_e32 v21, v30, v31
	v_add_f32_e32 v18, v20, v18
	v_add_f32_e32 v19, v19, v21
	v_add_f32_e32 v18, v18, v19
	ds_bpermute_b32 v19, v122, v18
	v_cvt_pk_bf16_f32 v20, v22, v23
	v_cvt_pk_bf16_f32 v21, v24, v25
	v_cvt_pk_bf16_f32 v22, v28, v29
	v_cvt_pk_bf16_f32 v23, v26, v27
	s_waitcnt lgkmcnt(0)
	v_add_f32_e32 v18, v18, v19
	ds_bpermute_b32 v19, v116, v18
	global_store_dwordx4 v[40:41], v[20:23], off
	s_and_saveexec_b64 s[24:25], s[2:3]
	s_cbranch_execz .LBB0_971
	s_waitcnt lgkmcnt(0)
	v_add_f32_e32 v20, v18, v19
	v_lshl_add_u64 v[18:19], v[34:35], 2, s[10:11]
	global_atomic_add_f32 v[18:19], v20, off
.LBB0_971:
	s_or_b64 exec, exec, s[24:25]
	v_add_u32_e32 v18, 0xb0, v148
	s_waitcnt lgkmcnt(0)
	v_ashrrev_i32_e32 v19, 31, v18
	v_lshlrev_b64 v[20:21], 11, v[18:19]
	v_lshl_add_u64 v[20:21], s[92:93], 0, v[20:21]
	v_lshl_add_u64 v[24:25], v[146:147], 1, v[20:21]
	s_nop 0
	v_mul_f32_e32 v14, 0xbfb8aa3b, v14
	v_mul_f32_e32 v15, 0xbfb8aa3b, v15
	v_mul_f32_e32 v16, 0xbfb8aa3b, v16
	v_mul_f32_e32 v17, 0xbfb8aa3b, v17
	v_mul_f32_e32 v6, 0xbfb8aa3b, v6
	v_mul_f32_e32 v7, 0xbfb8aa3b, v7
	v_mul_f32_e32 v8, 0xbfb8aa3b, v8
	v_mul_f32_e32 v9, 0xbfb8aa3b, v9
	v_exp_f32_e32 v14, v14
	v_exp_f32_e32 v15, v15
	v_exp_f32_e32 v16, v16
	v_exp_f32_e32 v17, v17
	v_exp_f32_e32 v6, v6
	v_exp_f32_e32 v7, v7
	v_exp_f32_e32 v8, v8
	v_exp_f32_e32 v9, v9
	v_add_f32_e32 v14, 1.0, v14
	v_add_f32_e32 v15, 1.0, v15
	v_add_f32_e32 v16, 1.0, v16
	v_add_f32_e32 v17, 1.0, v17
	v_add_f32_e32 v26, 1.0, v6
	v_add_f32_e32 v27, 1.0, v7
	v_add_f32_e32 v28, 1.0, v8
	v_add_f32_e32 v29, 1.0, v9
	v_rcp_f32_e32 v6, v14
	v_rcp_f32_e32 v7, v15
	v_rcp_f32_e32 v8, v16
	v_rcp_f32_e32 v9, v17
	v_rcp_f32_e32 v14, v26
	v_rcp_f32_e32 v15, v27
	v_rcp_f32_e32 v16, v28
	v_rcp_f32_e32 v17, v29
	s_waitcnt vmcnt(7)
	v_lshlrev_b32_e32 v26, 16, v206
	v_and_b32_e32 v27, 0xffff0000, v206
	v_lshlrev_b32_e32 v20, 16, v207
	v_and_b32_e32 v21, 0xffff0000, v207
	v_lshlrev_b32_e32 v28, 16, v208
	v_and_b32_e32 v29, 0xffff0000, v208
	v_lshlrev_b32_e32 v22, 16, v209
	v_and_b32_e32 v23, 0xffff0000, v209
	v_pk_fma_f32 v[8:9], v[12:13], v[8:9], v[20:21]
	v_pk_fma_f32 v[6:7], v[10:11], v[6:7], v[26:27]
	v_pk_fma_f32 v[10:11], v[4:5], v[16:17], v[22:23]
	v_pk_fma_f32 v[12:13], v[2:3], v[14:15], v[28:29]
	v_pk_mul_f32 v[2:3], v[8:9], v[8:9]
	v_pk_mul_f32 v[4:5], v[6:7], v[6:7]
	v_pk_mul_f32 v[14:15], v[10:11], v[10:11]
	v_pk_mul_f32 v[16:17], v[12:13], v[12:13]
	v_add_f32_e32 v4, v4, v5
	v_add_f32_e32 v2, v2, v3
	v_add_f32_e32 v3, v16, v17
	v_add_f32_e32 v5, v14, v15
	v_add_f32_e32 v2, v4, v2
	v_add_f32_e32 v3, v3, v5
	v_add_f32_e32 v2, v2, v3
	ds_bpermute_b32 v3, v122, v2
	v_cvt_pk_bf16_f32 v4, v6, v7
	v_cvt_pk_bf16_f32 v5, v8, v9
	v_cvt_pk_bf16_f32 v6, v12, v13
	v_cvt_pk_bf16_f32 v7, v10, v11
	s_waitcnt lgkmcnt(0)
	v_add_f32_e32 v2, v2, v3
	ds_bpermute_b32 v3, v116, v2
	global_store_dwordx4 v[24:25], v[4:7], off
	s_and_saveexec_b64 s[24:25], s[2:3]
	s_cbranch_execz .LBB0_973
	s_waitcnt lgkmcnt(0)
	v_add_f32_e32 v4, v2, v3
	v_lshl_add_u64 v[2:3], v[18:19], 2, s[10:11]
	global_atomic_add_f32 v[2:3], v4, off

.LBB0_1574:
	v_lshl_add_u32 v168, s24, 8, v172
	v_ashrrev_i32_e32 v169, 31, v168
	v_lshl_add_u64 v[50:51], v[168:169], 2, s[6:7]
	global_load_dword v218, v[50:51], off
	v_or_b32_e32 v236, 16, v168
	v_ashrrev_i32_e32 v237, 31, v236
	v_lshl_add_u64 v[238:239], v[236:237], 2, s[6:7]
	global_load_dword v219, v[238:239], off
	v_or_b32_e32 v240, 32, v168
	v_ashrrev_i32_e32 v241, 31, v240
	v_lshl_add_u64 v[242:243], v[240:241], 2, s[6:7]
	global_load_dword v220, v[242:243], off
	v_or_b32_e32 v246, 48, v168
	v_ashrrev_i32_e32 v247, 31, v246
	v_lshl_add_u64 v[248:249], v[246:247], 2, s[6:7]
	global_load_dword v221, v[248:249], off
	v_add_u32_e32 v250, 0x80, v168
	v_ashrrev_i32_e32 v251, 31, v250
	v_lshl_add_u64 v[252:253], v[250:251], 2, s[6:7]
	global_load_dword v222, v[252:253], off
	v_add_u32_e32 v254, 0x90, v168
	v_ashrrev_i32_e32 v255, 31, v254
	v_lshl_add_u64 v[236:237], v[254:255], 2, s[6:7]
	global_load_dword v223, v[236:237], off
	v_add_u32_e32 v238, 0xa0, v168
	v_ashrrev_i32_e32 v239, 31, v238
	v_lshl_add_u64 v[240:241], v[238:239], 2, s[6:7]
	global_load_dword v224, v[240:241], off
	v_add_u32_e32 v242, 0xb0, v168
	v_ashrrev_i32_e32 v243, 31, v242
	v_lshl_add_u64 v[246:247], v[242:243], 2, s[6:7]
	global_load_dword v225, v[246:247], off
	s_nop 0
	global_load_dwordx4 v[70:73], v[158:159], off
	global_load_dwordx4 v[66:69], v[158:159], off offset:128
	global_load_dwordx4 v[54:57], v[158:159], off offset:16
	s_nop 0
	global_load_dwordx4 v[50:53], v[158:159], off offset:144
	v_and_b32_e32 v171, 64, v178
	v_xor_b32_e32 v154, 16, v178
	v_add_u32_e32 v217, 64, v171
	v_cmp_lt_i32_e32 vcc, v154, v217
	v_and_or_b32 v182, v168, s49, 16
	v_xor_b32_e32 v216, 32, v178
	v_cndmask_b32_e32 v154, v178, v154, vcc
	v_cmp_gt_i32_e32 vcc, s40, v168
	v_lshl_or_b32 v170, s55, 8, v174
	v_ashrrev_i32_e32 v171, 31, v170
	v_cndmask_b32_e32 v184, v1, v182, vcc
	v_lshlrev_b32_e32 v182, 2, v154
	v_lshlrev_b32_e32 v154, 8, v184
	v_lshl_add_u64 v[196:197], v[156:157], 0, v[154:155]
	global_load_dwordx4 v[184:187], v[196:197], off
	global_load_dwordx4 v[188:191], v[196:197], off offset:48
	global_load_dwordx4 v[192:195], v[196:197], off offset:32
	s_nop 0
	global_load_dwordx4 v[196:199], v[196:197], off offset:16
	v_cmp_lt_i32_e32 vcc, v216, v217
	s_waitcnt vmcnt(0)
	v_fmamk_f32 v154, v218, 0x3a800000, v179
	v_rsq_f32_e32 v154, v154
	s_nop 0
	v_pk_mul_f32 v[142:143], v[142:143], v[154:155] op_sel_hi:[1,0]
	v_pk_mul_f32 v[138:139], v[138:139], v[154:155] op_sel_hi:[1,0]
	v_pk_mul_f32 v[134:135], v[134:135], v[154:155] op_sel_hi:[1,0]
	v_pk_mul_f32 v[130:131], v[130:131], v[154:155] op_sel_hi:[1,0]
	v_mov_b32_e32 v202, v143
	v_mov_b32_e32 v203, v139
	v_pk_mul_f32 v[144:145], v[144:145], v[154:155] op_sel_hi:[1,0]
	v_pk_mul_f32 v[140:141], v[140:141], v[154:155] op_sel_hi:[1,0]
	v_pk_mul_f32 v[200:201], v[132:133], v[154:155] op_sel_hi:[1,0]
	v_mov_b32_e32 v132, v142
	v_mov_b32_e32 v133, v138
	v_mov_b32_e32 v210, v131
	v_mov_b32_e32 v211, v135
	v_pk_mul_f32 v[202:203], v[202:203], v[202:203]
	v_pk_mul_f32 v[136:137], v[136:137], v[154:155] op_sel_hi:[1,0]
	v_mov_b32_e32 v204, v144
	v_mov_b32_e32 v205, v140
	v_mov_b32_e32 v208, v130
	v_mov_b32_e32 v209, v134
	v_pk_mul_f32 v[210:211], v[210:211], v[210:211]
	v_pk_fma_f32 v[132:133], v[132:133], v[132:133], v[202:203]
	v_mov_b32_e32 v206, v145
	v_mov_b32_e32 v207, v141
	v_mov_b32_e32 v212, v200
	v_mov_b32_e32 v213, v136
	v_pk_fma_f32 v[202:203], v[208:209], v[208:209], v[210:211]
	v_pk_fma_f32 v[132:133], v[204:205], v[204:205], v[132:133]
	v_mov_b32_e32 v214, v201
	v_mov_b32_e32 v215, v137
	v_pk_fma_f32 v[202:203], v[212:213], v[212:213], v[202:203]
	v_pk_fma_f32 v[132:133], v[206:207], v[206:207], v[132:133]
	v_pk_fma_f32 v[202:203], v[214:215], v[214:215], v[202:203]
	v_add_f32_e32 v132, v132, v133
	v_add_f32_e32 v132, v203, v132
	v_add_f32_e32 v133, v202, v132
	ds_bpermute_b32 v154, v182, v133
	v_cndmask_b32_e32 v132, v178, v216, vcc
	v_lshlrev_b32_e32 v132, 2, v132
	v_pk_mul_f32 v[142:143], v[70:71], v[142:143]
	v_pk_mul_f32 v[134:135], v[66:67], v[134:135]
	s_waitcnt lgkmcnt(0)
	v_add_f32_e32 v133, v133, v154
	ds_bpermute_b32 v154, v132, v133
	v_pk_mul_f32 v[144:145], v[72:73], v[144:145]
	v_pk_mul_f32 v[136:137], v[68:69], v[136:137]
	v_pk_mul_f32 v[138:139], v[54:55], v[138:139]
	v_pk_mul_f32 v[130:131], v[50:51], v[130:131]
	s_waitcnt lgkmcnt(0)
	v_add_f32_e32 v133, v133, v154
	v_fmamk_f32 v133, v133, 0x3c800000, v179
	v_rsq_f32_e32 v133, v133
	v_pk_mul_f32 v[140:141], v[56:57], v[140:141]
	v_pk_mul_f32 v[200:201], v[52:53], v[200:201]
	v_mul_f32_e32 v154, 0x3e000000, v133
	v_pk_mul_f32 v[142:143], v[142:143], v[154:155] op_sel_hi:[1,0]
	v_pk_mul_f32 v[134:135], v[134:135], v[154:155] op_sel_hi:[1,0]
	v_pk_mul_f32 v[144:145], v[144:145], v[154:155] op_sel_hi:[1,0]
	v_pk_mul_f32 v[136:137], v[136:137], v[154:155] op_sel_hi:[1,0]
	v_pk_mul_f32 v[138:139], v[138:139], v[154:155] op_sel_hi:[1,0]
	v_pk_mul_f32 v[130:131], v[130:131], v[154:155] op_sel_hi:[1,0]
	v_mov_b32_e32 v203, v134
	v_mov_b32_e32 v204, v134
	v_mov_b32_e32 v134, v143
	v_mov_b32_e32 v202, v142
	v_mov_b32_e32 v205, v142
	v_mov_b32_e32 v142, v135
	v_mov_b32_e32 v207, v136
	v_mov_b32_e32 v208, v136
	v_mov_b32_e32 v136, v145
	v_mov_b32_e32 v210, v138
	v_mov_b32_e32 v211, v130
	v_pk_mul_f32 v[134:135], v[186:187], v[134:135]
	v_mov_b32_e32 v206, v144
	v_mov_b32_e32 v209, v144
	v_mov_b32_e32 v144, v137
	v_pk_mul_f32 v[136:137], v[198:199], v[136:137]
	v_sub_f32_e32 v183, v134, v135
	v_pk_mul_f32 v[134:135], v[192:193], v[210:211]
	v_sub_f32_e32 v136, v136, v137
	v_sub_f32_e32 v137, v134, v135
	v_mov_b32_e32 v134, v130
	v_mov_b32_e32 v135, v138
	v_pk_mul_f32 v[144:145], v[198:199], v[144:145]
	v_pk_mul_f32 v[134:135], v[192:193], v[134:135]
	v_mov_b32_e32 v130, v139
	v_mov_b32_e32 v138, v131
	v_pk_mul_f32 v[140:141], v[140:141], v[154:155] op_sel_hi:[1,0]
	v_pk_mul_f32 v[200:201], v[200:201], v[154:155] op_sel_hi:[1,0]
	v_pk_mul_f32 v[142:143], v[186:187], v[142:143]
	v_pk_mul_f32 v[186:187], v[196:197], v[206:207]
	v_add_f32_e32 v144, v145, v144
	v_add_f32_e32 v145, v135, v134
	v_pk_mul_f32 v[134:135], v[194:195], v[130:131]
	v_pk_mul_f32 v[130:131], v[194:195], v[138:139]
	v_add_f32_e32 v142, v143, v142
	v_sub_f32_e32 v143, v186, v187
	v_add_f32_e32 v186, v131, v130
	v_mov_b32_e32 v130, v140
	v_mov_b32_e32 v131, v200
	v_pk_mul_f32 v[130:131], v[188:189], v[130:131]
	v_pk_mul_f32 v[202:203], v[184:185], v[202:203]
	v_sub_f32_e32 v187, v130, v131
	v_mov_b32_e32 v130, v200
	v_mov_b32_e32 v131, v140
	v_pk_mul_f32 v[130:131], v[188:189], v[130:131]
	v_mov_b32_e32 v200, v141
	v_add_f32_e32 v188, v131, v130
	v_pk_mul_f32 v[130:131], v[190:191], v[200:201]
	v_mov_b32_e32 v140, v201
	v_sub_f32_e32 v189, v130, v131
	v_pk_mul_f32 v[130:131], v[190:191], v[140:141]
	v_pk_mul_f32 v[184:185], v[184:185], v[204:205]
	v_add_f32_e32 v140, v131, v130
	v_lshlrev_b64 v[130:131], 11, v[168:169]
	v_add_f32_e32 v154, v185, v184
	v_sub_f32_e32 v185, v134, v135
	v_lshl_add_u64 v[134:135], s[44:45], 0, v[130:131]
	v_lshlrev_b64 v[130:131], 1, v[170:171]
	v_pk_mul_f32 v[196:197], v[196:197], v[208:209]
	v_sub_f32_e32 v133, v202, v203
	v_lshl_add_u64 v[138:139], v[134:135], 0, v[130:131]
	v_cvt_pk_bf16_f32 v134, v133, v183
	v_cvt_pk_bf16_f32 v135, v143, v136
	v_or_b32_e32 v170, 16, v168
	v_add_f32_e32 v184, v197, v196
	v_cvt_pk_bf16_f32 v136, v137, v185
	v_cvt_pk_bf16_f32 v137, v187, v189
	global_store_dwordx4 v[138:139], v[134:137], off
	v_ashrrev_i32_e32 v171, 31, v170
	v_cmp_gt_i32_e32 vcc, s40, v170
	v_cvt_pk_bf16_f32 v134, v154, v142
	v_cvt_pk_bf16_f32 v135, v184, v144
	v_cvt_pk_bf16_f32 v136, v145, v186
	v_cvt_pk_bf16_f32 v137, v188, v140
	global_store_dwordx4 v[138:139], v[134:137], off offset:64
	s_nop 1
	v_lshl_add_u64 v[134:135], v[170:171], 2, s[6:7]
	s_nop 0
	v_bitop3_b32 v134, v168, s52, 16 bitop3:0xc8
	v_add_u32_e32 v134, 16, v134
	v_cndmask_b32_e32 v134, v1, v134, vcc
	v_lshlrev_b32_e32 v154, 8, v134
	v_lshl_add_u64 v[184:185], v[156:157], 0, v[154:155]
	global_load_dwordx4 v[134:137], v[184:185], off
	global_load_dwordx4 v[138:141], v[184:185], off offset:16
	global_load_dwordx4 v[142:145], v[184:185], off offset:32
	s_nop 0
	global_load_dwordx4 v[184:187], v[184:185], off offset:48
	s_waitcnt vmcnt(6)
	v_fmamk_f32 v133, v219, 0x3a800000, v179
	v_rsq_f32_e32 v154, v133
	s_nop 0
	v_pk_mul_f32 v[126:127], v[126:127], v[154:155] op_sel_hi:[1,0]
	v_pk_mul_f32 v[122:123], v[122:123], v[154:155] op_sel_hi:[1,0]
	v_pk_mul_f32 v[118:119], v[118:119], v[154:155] op_sel_hi:[1,0]
	v_pk_mul_f32 v[114:115], v[114:115], v[154:155] op_sel_hi:[1,0]
	v_mov_b32_e32 v190, v127
	v_mov_b32_e32 v191, v123
	v_pk_mul_f32 v[128:129], v[128:129], v[154:155] op_sel_hi:[1,0]
	v_pk_mul_f32 v[124:125], v[124:125], v[154:155] op_sel_hi:[1,0]
	v_mov_b32_e32 v188, v126
	v_mov_b32_e32 v189, v122
	v_mov_b32_e32 v198, v115
	v_mov_b32_e32 v199, v119
	v_pk_mul_f32 v[190:191], v[190:191], v[190:191]
	v_pk_mul_f32 v[120:121], v[120:121], v[154:155] op_sel_hi:[1,0]
	v_pk_mul_f32 v[116:117], v[116:117], v[154:155] op_sel_hi:[1,0]
	v_mov_b32_e32 v192, v128
	v_mov_b32_e32 v193, v124
	v_mov_b32_e32 v196, v114
	v_mov_b32_e32 v197, v118
	v_pk_mul_f32 v[198:199], v[198:199], v[198:199]
	v_pk_fma_f32 v[188:189], v[188:189], v[188:189], v[190:191]
	v_mov_b32_e32 v194, v129
	v_mov_b32_e32 v195, v125
	v_mov_b32_e32 v200, v116
	v_mov_b32_e32 v201, v120
	v_pk_fma_f32 v[190:191], v[196:197], v[196:197], v[198:199]
	v_pk_fma_f32 v[188:189], v[192:193], v[192:193], v[188:189]
	v_mov_b32_e32 v202, v117
	v_mov_b32_e32 v203, v121
	v_pk_fma_f32 v[190:191], v[200:201], v[200:201], v[190:191]
	v_pk_fma_f32 v[188:189], v[194:195], v[194:195], v[188:189]
	v_pk_fma_f32 v[190:191], v[202:203], v[202:203], v[190:191]
	v_add_f32_e32 v133, v188, v189
	v_add_f32_e32 v133, v191, v133
	v_add_f32_e32 v133, v190, v133
	ds_bpermute_b32 v154, v182, v133
	v_pk_mul_f32 v[126:127], v[70:71], v[126:127]
	v_pk_mul_f32 v[118:119], v[66:67], v[118:119]
	v_pk_mul_f32 v[128:129], v[72:73], v[128:129]
	v_pk_mul_f32 v[120:121], v[68:69], v[120:121]
	s_waitcnt lgkmcnt(0)
	v_add_f32_e32 v133, v133, v154
	ds_bpermute_b32 v154, v132, v133
	v_pk_mul_f32 v[114:115], v[50:51], v[114:115]
	v_pk_mul_f32 v[116:117], v[52:53], v[116:117]
	s_waitcnt lgkmcnt(0)
	v_add_f32_e32 v133, v133, v154
	v_fmamk_f32 v133, v133, 0x3c800000, v179
	v_rsq_f32_e32 v133, v133
	s_nop 0
	v_mul_f32_e32 v154, 0x3e000000, v133
	v_pk_mul_f32 v[126:127], v[126:127], v[154:155] op_sel_hi:[1,0]
	v_pk_mul_f32 v[118:119], v[118:119], v[154:155] op_sel_hi:[1,0]
	v_mov_b32_e32 v188, v126
	v_mov_b32_e32 v189, v118
	v_mov_b32_e32 v190, v118
	v_mov_b32_e32 v191, v126
	v_mov_b32_e32 v118, v127
	v_pk_mul_f32 v[128:129], v[128:129], v[154:155] op_sel_hi:[1,0]
	v_pk_mul_f32 v[120:121], v[120:121], v[154:155] op_sel_hi:[1,0]
	v_mov_b32_e32 v126, v119
	s_waitcnt vmcnt(3)
	v_pk_mul_f32 v[188:189], v[134:135], v[188:189]
	v_pk_mul_f32 v[134:135], v[134:135], v[190:191]
	v_pk_mul_f32 v[118:119], v[136:137], v[118:119]
	v_add_f32_e32 v134, v135, v134
	v_sub_f32_e32 v135, v118, v119
	v_mov_b32_e32 v118, v128
	v_mov_b32_e32 v119, v120
	v_pk_mul_f32 v[126:127], v[136:137], v[126:127]
	s_waitcnt vmcnt(2)
	v_pk_mul_f32 v[118:119], v[138:139], v[118:119]
	v_add_f32_e32 v126, v127, v126
	v_sub_f32_e32 v127, v118, v119
	v_mov_b32_e32 v118, v120
	v_mov_b32_e32 v119, v128
	v_pk_mul_f32 v[118:119], v[138:139], v[118:119]
	v_mov_b32_e32 v120, v129
	v_add_f32_e32 v136, v119, v118
	v_pk_mul_f32 v[118:119], v[140:141], v[120:121]
	v_mov_b32_e32 v128, v121
	v_sub_f32_e32 v137, v118, v119
	v_pk_mul_f32 v[118:119], v[140:141], v[128:129]
	v_pk_mul_f32 v[114:115], v[114:115], v[154:155] op_sel_hi:[1,0]
	v_add_f32_e32 v128, v119, v118
	v_pk_mul_f32 v[118:119], v[54:55], v[122:123]
	v_mov_b32_e32 v123, v114
	v_pk_mul_f32 v[118:119], v[118:119], v[154:155] op_sel_hi:[1,0]
	v_pk_mul_f32 v[120:121], v[56:57], v[124:125]
	v_mov_b32_e32 v122, v118
	s_waitcnt vmcnt(1)
	v_pk_mul_f32 v[122:123], v[142:143], v[122:123]
	v_pk_mul_f32 v[120:121], v[120:121], v[154:155] op_sel_hi:[1,0]
	v_sub_f32_e32 v124, v122, v123
	v_mov_b32_e32 v122, v114
	v_mov_b32_e32 v123, v118
	v_pk_mul_f32 v[122:123], v[142:143], v[122:123]
	v_mov_b32_e32 v114, v119
	v_mov_b32_e32 v118, v115
	v_pk_mul_f32 v[116:117], v[116:117], v[154:155] op_sel_hi:[1,0]
	v_add_f32_e32 v125, v123, v122
	v_pk_mul_f32 v[122:123], v[144:145], v[114:115]
	v_pk_mul_f32 v[114:115], v[144:145], v[118:119]
	v_sub_f32_e32 v122, v122, v123
	v_add_f32_e32 v123, v115, v114
	v_mov_b32_e32 v114, v120
	v_mov_b32_e32 v115, v116
	s_waitcnt vmcnt(0)
	v_pk_mul_f32 v[114:115], v[184:185], v[114:115]
	v_sub_f32_e32 v133, v188, v189
	v_sub_f32_e32 v129, v114, v115
	v_mov_b32_e32 v114, v116
	v_mov_b32_e32 v115, v120
	v_pk_mul_f32 v[114:115], v[184:185], v[114:115]
	v_mov_b32_e32 v116, v121
	v_add_f32_e32 v138, v115, v114
	v_pk_mul_f32 v[114:115], v[186:187], v[116:117]
	v_mov_b32_e32 v120, v117
	v_sub_f32_e32 v139, v114, v115
	v_pk_mul_f32 v[114:115], v[186:187], v[120:121]
	s_nop 0
	v_add_f32_e32 v120, v115, v114
	v_lshlrev_b64 v[114:115], 11, v[170:171]
	v_lshl_add_u64 v[114:115], s[44:45], 0, v[114:115]
	v_lshl_add_u64 v[118:119], v[114:115], 0, v[130:131]
	v_cvt_pk_bf16_f32 v114, v133, v135
	v_cvt_pk_bf16_f32 v115, v127, v137
	v_cvt_pk_bf16_f32 v116, v124, v122
	v_cvt_pk_bf16_f32 v117, v129, v139
	global_store_dwordx4 v[118:119], v[114:117], off
	s_nop 1
	v_cvt_pk_bf16_f32 v114, v134, v126
	v_or_b32_e32 v126, 32, v168
	v_cvt_pk_bf16_f32 v115, v136, v128
	v_ashrrev_i32_e32 v127, 31, v126
	v_cvt_pk_bf16_f32 v116, v125, v123
	v_cvt_pk_bf16_f32 v117, v138, v120
	global_store_dwordx4 v[118:119], v[114:117], off offset:64
	v_cmp_gt_i32_e32 vcc, s40, v126
	s_nop 0
	v_lshl_add_u64 v[114:115], v[126:127], 2, s[6:7]
	s_nop 0
	v_and_or_b32 v114, v126, s53, 16
	v_cndmask_b32_e32 v114, v1, v114, vcc
	v_lshlrev_b32_e32 v154, 8, v114
	v_lshl_add_u64 v[128:129], v[156:157], 0, v[154:155]
	global_load_dwordx4 v[114:117], v[128:129], off
	s_waitcnt vmcnt(3)
	v_fmamk_f32 v118, v220, 0x3a800000, v179
	v_rsq_f32_e32 v134, v118
	global_load_dwordx4 v[118:121], v[128:129], off offset:16
	global_load_dwordx4 v[122:125], v[128:129], off offset:32
	v_pk_mul_f32 v[110:111], v[110:111], v[134:135] op_sel_hi:[1,0]
	v_pk_mul_f32 v[106:107], v[106:107], v[134:135] op_sel_hi:[1,0]
	v_pk_mul_f32 v[136:137], v[100:101], v[134:135] op_sel_hi:[1,0]
	v_mov_b32_e32 v100, v111
	v_mov_b32_e32 v101, v107
	v_pk_mul_f32 v[112:113], v[112:113], v[134:135] op_sel_hi:[1,0]
	v_pk_mul_f32 v[108:109], v[108:109], v[134:135] op_sel_hi:[1,0]
	v_pk_mul_f32 v[104:105], v[104:105], v[134:135] op_sel_hi:[1,0]
	v_pk_mul_f32 v[102:103], v[102:103], v[134:135] op_sel_hi:[1,0]
	v_pk_mul_f32 v[134:135], v[98:99], v[134:135] op_sel_hi:[1,0]
	v_mov_b32_e32 v98, v110
	v_mov_b32_e32 v99, v106
	v_pk_mul_f32 v[100:101], v[100:101], v[100:101]
	v_mov_b32_e32 v138, v135
	v_pk_fma_f32 v[98:99], v[98:99], v[98:99], v[100:101]
	v_mov_b32_e32 v100, v112
	v_mov_b32_e32 v101, v108
	v_pk_fma_f32 v[98:99], v[100:101], v[100:101], v[98:99]
	v_mov_b32_e32 v100, v113
	v_mov_b32_e32 v101, v109
	v_mov_b32_e32 v139, v103
	v_pk_fma_f32 v[98:99], v[100:101], v[100:101], v[98:99]
	v_mov_b32_e32 v100, v134
	v_mov_b32_e32 v101, v102
	v_pk_mul_f32 v[138:139], v[138:139], v[138:139]
	v_add_f32_e32 v98, v98, v99
	v_pk_fma_f32 v[100:101], v[100:101], v[100:101], v[138:139]
	v_mov_b32_e32 v138, v136
	v_mov_b32_e32 v139, v104
	v_pk_fma_f32 v[100:101], v[138:139], v[138:139], v[100:101]
	v_mov_b32_e32 v138, v137
	v_mov_b32_e32 v139, v105
	v_pk_fma_f32 v[138:139], v[138:139], v[138:139], v[100:101]
	v_pk_mul_f32 v[110:111], v[70:71], v[110:111]
	v_add_f32_e32 v133, v139, v98
	global_load_dwordx4 v[98:101], v[128:129], off offset:48
	v_add_f32_e32 v128, v138, v133
	ds_bpermute_b32 v129, v182, v128
	v_pk_mul_f32 v[102:103], v[66:67], v[102:103]
	v_pk_mul_f32 v[112:113], v[72:73], v[112:113]
	v_pk_mul_f32 v[104:105], v[68:69], v[104:105]
	s_waitcnt lgkmcnt(0)
	v_add_f32_e32 v128, v128, v129
	ds_bpermute_b32 v129, v132, v128
	s_waitcnt lgkmcnt(0)
	v_add_f32_e32 v128, v128, v129
	v_fmamk_f32 v128, v128, 0x3c800000, v179
	v_rsq_f32_e32 v128, v128
	s_nop 0
	v_mul_f32_e32 v128, 0x3e000000, v128
	v_pk_mul_f32 v[110:111], v[110:111], v[128:129] op_sel_hi:[1,0]
	v_pk_mul_f32 v[102:103], v[102:103], v[128:129] op_sel_hi:[1,0]
	v_mov_b32_e32 v138, v110
	v_mov_b32_e32 v139, v102
	s_waitcnt vmcnt(3)
	v_pk_mul_f32 v[138:139], v[114:115], v[138:139]
	v_pk_mul_f32 v[112:113], v[112:113], v[128:129] op_sel_hi:[1,0]
	v_pk_mul_f32 v[104:105], v[104:105], v[128:129] op_sel_hi:[1,0]
	v_sub_f32_e32 v129, v138, v139
	v_mov_b32_e32 v138, v102
	v_mov_b32_e32 v139, v110
	v_pk_mul_f32 v[114:115], v[114:115], v[138:139]
	v_mov_b32_e32 v102, v111
	v_mov_b32_e32 v110, v103
	v_add_f32_e32 v133, v115, v114
	v_pk_mul_f32 v[114:115], v[116:117], v[102:103]
	v_pk_mul_f32 v[102:103], v[116:117], v[110:111]
	v_sub_f32_e32 v114, v114, v115
	v_add_f32_e32 v115, v103, v102
	v_mov_b32_e32 v102, v112
	v_mov_b32_e32 v103, v104
	s_waitcnt vmcnt(2)
	v_pk_mul_f32 v[102:103], v[118:119], v[102:103]
	s_nop 0
	v_sub_f32_e32 v116, v102, v103
	v_mov_b32_e32 v102, v104
	v_mov_b32_e32 v103, v112
	v_pk_mul_f32 v[102:103], v[118:119], v[102:103]
	v_mov_b32_e32 v104, v113
	v_add_f32_e32 v117, v103, v102
	v_pk_mul_f32 v[102:103], v[120:121], v[104:105]
	v_mov_b32_e32 v112, v105
	v_sub_f32_e32 v118, v102, v103
	v_pk_mul_f32 v[102:103], v[120:121], v[112:113]
	v_pk_mul_f32 v[104:105], v[56:57], v[108:109]
	v_add_f32_e32 v112, v103, v102
	v_pk_mul_f32 v[102:103], v[54:55], v[106:107]
	v_pk_mul_f32 v[106:107], v[50:51], v[134:135]
	v_pk_mul_f32 v[102:103], v[102:103], v[128:129] op_sel_hi:[1,0]
	v_pk_mul_f32 v[106:107], v[106:107], v[128:129] op_sel_hi:[1,0]
	v_mov_b32_e32 v110, v102
	v_mov_b32_e32 v111, v106
	s_waitcnt vmcnt(1)
	v_pk_mul_f32 v[110:111], v[122:123], v[110:111]
	v_pk_mul_f32 v[108:109], v[52:53], v[136:137]
	v_sub_f32_e32 v113, v110, v111
	v_mov_b32_e32 v110, v106
	v_mov_b32_e32 v111, v102
	v_mov_b32_e32 v102, v107
	v_pk_mul_f32 v[104:105], v[104:105], v[128:129] op_sel_hi:[1,0]
	v_pk_mul_f32 v[108:109], v[108:109], v[128:129] op_sel_hi:[1,0]
	v_pk_mul_f32 v[110:111], v[122:123], v[110:111]
	v_mov_b32_e32 v106, v103
	v_pk_mul_f32 v[102:103], v[124:125], v[102:103]
	v_add_f32_e32 v119, v111, v110
	v_pk_mul_f32 v[110:111], v[124:125], v[106:107]
	v_add_f32_e32 v107, v103, v102
	v_mov_b32_e32 v102, v104
	v_mov_b32_e32 v103, v108
	v_sub_f32_e32 v106, v110, v111
	s_waitcnt vmcnt(0)
	v_pk_mul_f32 v[102:103], v[98:99], v[102:103]
	s_nop 0
	v_sub_f32_e32 v110, v102, v103
	v_mov_b32_e32 v102, v108
	v_mov_b32_e32 v103, v104
	v_pk_mul_f32 v[98:99], v[98:99], v[102:103]
	v_mov_b32_e32 v108, v105
	v_add_f32_e32 v111, v99, v98
	v_pk_mul_f32 v[98:99], v[100:101], v[108:109]
	v_mov_b32_e32 v104, v109
	v_sub_f32_e32 v108, v98, v99
	v_pk_mul_f32 v[98:99], v[100:101], v[104:105]
	s_nop 0
	v_add_f32_e32 v104, v99, v98
	v_lshlrev_b64 v[98:99], 11, v[126:127]
	v_lshl_add_u64 v[98:99], s[44:45], 0, v[98:99]
	v_lshl_add_u64 v[102:103], v[98:99], 0, v[130:131]
	v_cvt_pk_bf16_f32 v98, v129, v114
	v_cvt_pk_bf16_f32 v99, v116, v118
	v_cvt_pk_bf16_f32 v100, v113, v106
	v_cvt_pk_bf16_f32 v101, v110, v108
	v_or_b32_e32 v110, 48, v168
	global_store_dwordx4 v[102:103], v[98:101], off
	v_cmp_gt_i32_e32 vcc, s40, v110
	s_nop 0
	v_cvt_pk_bf16_f32 v98, v133, v115
	v_cvt_pk_bf16_f32 v99, v117, v112
	v_cvt_pk_bf16_f32 v100, v119, v107
	v_cvt_pk_bf16_f32 v101, v111, v104
	v_ashrrev_i32_e32 v111, 31, v110
	global_store_dwordx4 v[102:103], v[98:101], off offset:64
	s_nop 1
	v_lshl_add_u64 v[98:99], v[110:111], 2, s[6:7]
	s_nop 0
	v_bitop3_b32 v98, v168, s54, 48 bitop3:0xc8
	v_add_u32_e32 v98, 16, v98
	v_cndmask_b32_e32 v98, v1, v98, vcc
	v_lshlrev_b32_e32 v154, 8, v98
	v_lshl_add_u64 v[112:113], v[156:157], 0, v[154:155]
	global_load_dwordx4 v[98:101], v[112:113], off
	s_waitcnt vmcnt(3)
	v_fmamk_f32 v102, v221, 0x3a800000, v179
	v_rsq_f32_e32 v114, v102
	global_load_dwordx4 v[102:105], v[112:113], off offset:16
	global_load_dwordx4 v[106:109], v[112:113], off offset:32
	v_pk_mul_f32 v[94:95], v[94:95], v[114:115] op_sel_hi:[1,0]
	v_pk_mul_f32 v[90:91], v[90:91], v[114:115] op_sel_hi:[1,0]
	v_pk_mul_f32 v[116:117], v[84:85], v[114:115] op_sel_hi:[1,0]
	v_mov_b32_e32 v84, v95
	v_mov_b32_e32 v85, v91
	v_pk_mul_f32 v[96:97], v[96:97], v[114:115] op_sel_hi:[1,0]
	v_pk_mul_f32 v[92:93], v[92:93], v[114:115] op_sel_hi:[1,0]
	v_pk_mul_f32 v[88:89], v[88:89], v[114:115] op_sel_hi:[1,0]
	v_pk_mul_f32 v[86:87], v[86:87], v[114:115] op_sel_hi:[1,0]
	v_pk_mul_f32 v[114:115], v[82:83], v[114:115] op_sel_hi:[1,0]
	v_mov_b32_e32 v82, v94
	v_mov_b32_e32 v83, v90
	v_pk_mul_f32 v[84:85], v[84:85], v[84:85]
	v_mov_b32_e32 v118, v115
	v_pk_fma_f32 v[82:83], v[82:83], v[82:83], v[84:85]
	v_mov_b32_e32 v84, v96
	v_mov_b32_e32 v85, v92
	v_pk_fma_f32 v[82:83], v[84:85], v[84:85], v[82:83]
	v_mov_b32_e32 v84, v97
	v_mov_b32_e32 v85, v93
	v_mov_b32_e32 v119, v87
	v_pk_fma_f32 v[82:83], v[84:85], v[84:85], v[82:83]
	v_mov_b32_e32 v84, v114
	v_mov_b32_e32 v85, v86
	v_pk_mul_f32 v[118:119], v[118:119], v[118:119]
	v_add_f32_e32 v82, v82, v83
	v_pk_fma_f32 v[84:85], v[84:85], v[84:85], v[118:119]
	v_mov_b32_e32 v118, v116
	v_mov_b32_e32 v119, v88
	v_pk_fma_f32 v[84:85], v[118:119], v[118:119], v[84:85]
	v_mov_b32_e32 v118, v117
	v_mov_b32_e32 v119, v89
	v_pk_fma_f32 v[118:119], v[118:119], v[118:119], v[84:85]
	v_pk_mul_f32 v[94:95], v[70:71], v[94:95]
	v_add_f32_e32 v119, v119, v82
	global_load_dwordx4 v[82:85], v[112:113], off offset:48
	v_add_f32_e32 v112, v118, v119
	ds_bpermute_b32 v113, v182, v112
	v_pk_mul_f32 v[86:87], v[66:67], v[86:87]
	v_pk_mul_f32 v[96:97], v[72:73], v[96:97]
	v_pk_mul_f32 v[88:89], v[68:69], v[88:89]
	s_waitcnt lgkmcnt(0)
	v_add_f32_e32 v112, v112, v113
	ds_bpermute_b32 v113, v132, v112
	s_waitcnt lgkmcnt(0)
	v_add_f32_e32 v112, v112, v113
	v_fmamk_f32 v112, v112, 0x3c800000, v179
	v_rsq_f32_e32 v112, v112
	s_nop 0
	v_mul_f32_e32 v112, 0x3e000000, v112
	v_pk_mul_f32 v[94:95], v[94:95], v[112:113] op_sel_hi:[1,0]
	v_pk_mul_f32 v[86:87], v[86:87], v[112:113] op_sel_hi:[1,0]
	v_mov_b32_e32 v118, v94
	v_mov_b32_e32 v119, v86
	s_waitcnt vmcnt(3)
	v_pk_mul_f32 v[118:119], v[98:99], v[118:119]
	v_pk_mul_f32 v[96:97], v[96:97], v[112:113] op_sel_hi:[1,0]
	v_pk_mul_f32 v[88:89], v[88:89], v[112:113] op_sel_hi:[1,0]
	v_sub_f32_e32 v113, v118, v119
	v_mov_b32_e32 v118, v86
	v_mov_b32_e32 v119, v94
	v_pk_mul_f32 v[98:99], v[98:99], v[118:119]
	v_mov_b32_e32 v86, v95
	v_mov_b32_e32 v94, v87
	v_add_f32_e32 v118, v99, v98
	v_pk_mul_f32 v[98:99], v[100:101], v[86:87]
	v_pk_mul_f32 v[86:87], v[100:101], v[94:95]
	v_sub_f32_e32 v98, v98, v99
	v_add_f32_e32 v99, v87, v86
	v_mov_b32_e32 v86, v96
	v_mov_b32_e32 v87, v88
	s_waitcnt vmcnt(2)
	v_pk_mul_f32 v[86:87], v[102:103], v[86:87]
	s_nop 0
	v_sub_f32_e32 v100, v86, v87
	v_mov_b32_e32 v86, v88
	v_mov_b32_e32 v87, v96
	v_pk_mul_f32 v[86:87], v[102:103], v[86:87]
	v_mov_b32_e32 v88, v97
	v_add_f32_e32 v101, v87, v86
	v_pk_mul_f32 v[86:87], v[104:105], v[88:89]
	v_mov_b32_e32 v96, v89
	v_sub_f32_e32 v102, v86, v87
	v_pk_mul_f32 v[86:87], v[104:105], v[96:97]
	v_pk_mul_f32 v[88:89], v[56:57], v[92:93]
	v_add_f32_e32 v96, v87, v86
	v_pk_mul_f32 v[86:87], v[54:55], v[90:91]
	v_pk_mul_f32 v[90:91], v[50:51], v[114:115]
	v_pk_mul_f32 v[86:87], v[86:87], v[112:113] op_sel_hi:[1,0]
	v_pk_mul_f32 v[90:91], v[90:91], v[112:113] op_sel_hi:[1,0]
	v_mov_b32_e32 v94, v86
	v_mov_b32_e32 v95, v90
	s_waitcnt vmcnt(1)
	v_pk_mul_f32 v[94:95], v[106:107], v[94:95]
	v_pk_mul_f32 v[92:93], v[52:53], v[116:117]
	v_sub_f32_e32 v97, v94, v95
	v_mov_b32_e32 v94, v90
	v_mov_b32_e32 v95, v86
	v_mov_b32_e32 v86, v91
	v_pk_mul_f32 v[88:89], v[88:89], v[112:113] op_sel_hi:[1,0]
	v_pk_mul_f32 v[92:93], v[92:93], v[112:113] op_sel_hi:[1,0]
	v_pk_mul_f32 v[94:95], v[106:107], v[94:95]
	v_mov_b32_e32 v90, v87
	v_pk_mul_f32 v[86:87], v[108:109], v[86:87]
	v_add_f32_e32 v103, v95, v94
	v_pk_mul_f32 v[94:95], v[108:109], v[90:91]
	v_add_f32_e32 v91, v87, v86
	v_mov_b32_e32 v86, v88
	v_mov_b32_e32 v87, v92
	v_sub_f32_e32 v90, v94, v95
	s_waitcnt vmcnt(0)
	v_pk_mul_f32 v[86:87], v[82:83], v[86:87]
	s_nop 0
	v_sub_f32_e32 v94, v86, v87
	v_mov_b32_e32 v86, v92
	v_mov_b32_e32 v87, v88
	v_pk_mul_f32 v[82:83], v[82:83], v[86:87]
	v_mov_b32_e32 v92, v89
	v_add_f32_e32 v95, v83, v82
	v_pk_mul_f32 v[82:83], v[84:85], v[92:93]
	v_mov_b32_e32 v88, v93
	v_sub_f32_e32 v92, v82, v83
	v_pk_mul_f32 v[82:83], v[84:85], v[88:89]
	s_nop 0
	v_add_f32_e32 v88, v83, v82
	v_lshlrev_b64 v[82:83], 11, v[110:111]
	v_lshl_add_u64 v[82:83], s[44:45], 0, v[82:83]
	v_lshl_add_u64 v[86:87], v[82:83], 0, v[130:131]
	v_cvt_pk_bf16_f32 v82, v113, v98
	v_cvt_pk_bf16_f32 v83, v100, v102
	v_cvt_pk_bf16_f32 v84, v97, v90
	v_cvt_pk_bf16_f32 v85, v94, v92
	v_add_u32_e32 v94, 0x80, v168
	global_store_dwordx4 v[86:87], v[82:85], off
	v_cmp_gt_i32_e32 vcc, s40, v94
	s_nop 0
	v_cvt_pk_bf16_f32 v82, v118, v99
	v_cvt_pk_bf16_f32 v83, v101, v96
	v_cvt_pk_bf16_f32 v84, v103, v91
	v_cvt_pk_bf16_f32 v85, v95, v88
	v_ashrrev_i32_e32 v95, 31, v94
	global_store_dwordx4 v[86:87], v[82:85], off offset:64
	s_nop 1
	v_lshl_add_u64 v[82:83], v[94:95], 2, s[6:7]
	s_nop 0
	v_and_or_b32 v82, v94, s49, 16
	v_cndmask_b32_e32 v82, v1, v82, vcc
	v_lshlrev_b32_e32 v154, 8, v82
	v_lshl_add_u64 v[96:97], v[156:157], 0, v[154:155]
	global_load_dwordx4 v[82:85], v[96:97], off
	s_waitcnt vmcnt(3)
	v_fmamk_f32 v86, v222, 0x3a800000, v179
	v_rsq_f32_e32 v98, v86
	global_load_dwordx4 v[86:89], v[96:97], off offset:16
	global_load_dwordx4 v[90:93], v[96:97], off offset:32
	v_pk_mul_f32 v[78:79], v[78:79], v[98:99] op_sel_hi:[1,0]
	v_pk_mul_f32 v[74:75], v[74:75], v[98:99] op_sel_hi:[1,0]
	v_pk_mul_f32 v[100:101], v[60:61], v[98:99] op_sel_hi:[1,0]
	v_mov_b32_e32 v60, v79
	v_mov_b32_e32 v61, v75
	v_pk_mul_f32 v[80:81], v[80:81], v[98:99] op_sel_hi:[1,0]
	v_pk_mul_f32 v[76:77], v[76:77], v[98:99] op_sel_hi:[1,0]
	v_pk_mul_f32 v[64:65], v[64:65], v[98:99] op_sel_hi:[1,0]
	v_pk_mul_f32 v[62:63], v[62:63], v[98:99] op_sel_hi:[1,0]
	v_pk_mul_f32 v[98:99], v[58:59], v[98:99] op_sel_hi:[1,0]
	v_mov_b32_e32 v58, v78
	v_mov_b32_e32 v59, v74
	v_pk_mul_f32 v[60:61], v[60:61], v[60:61]
	v_mov_b32_e32 v102, v99
	v_pk_fma_f32 v[58:59], v[58:59], v[58:59], v[60:61]
	v_mov_b32_e32 v60, v80
	v_mov_b32_e32 v61, v76
	v_pk_fma_f32 v[58:59], v[60:61], v[60:61], v[58:59]
	v_mov_b32_e32 v60, v81
	v_mov_b32_e32 v61, v77
	v_mov_b32_e32 v103, v63
	v_pk_fma_f32 v[58:59], v[60:61], v[60:61], v[58:59]
	v_mov_b32_e32 v60, v98
	v_mov_b32_e32 v61, v62
	v_pk_mul_f32 v[102:103], v[102:103], v[102:103]
	v_add_f32_e32 v58, v58, v59
	v_pk_fma_f32 v[60:61], v[60:61], v[60:61], v[102:103]
	v_mov_b32_e32 v102, v100
	v_mov_b32_e32 v103, v64
	v_pk_fma_f32 v[60:61], v[102:103], v[102:103], v[60:61]
	v_mov_b32_e32 v102, v101
	v_mov_b32_e32 v103, v65
	v_pk_fma_f32 v[102:103], v[102:103], v[102:103], v[60:61]
	v_pk_mul_f32 v[78:79], v[70:71], v[78:79]
	v_add_f32_e32 v103, v103, v58
	global_load_dwordx4 v[58:61], v[96:97], off offset:48
	v_add_f32_e32 v96, v102, v103
	ds_bpermute_b32 v97, v182, v96
	v_pk_mul_f32 v[62:63], v[66:67], v[62:63]
	v_pk_mul_f32 v[80:81], v[72:73], v[80:81]
	v_pk_mul_f32 v[64:65], v[68:69], v[64:65]
	s_waitcnt lgkmcnt(0)
	v_add_f32_e32 v96, v96, v97
	ds_bpermute_b32 v97, v132, v96
	s_waitcnt lgkmcnt(0)
	v_add_f32_e32 v96, v96, v97
	v_fmamk_f32 v96, v96, 0x3c800000, v179
	v_rsq_f32_e32 v96, v96
	s_nop 0
	v_mul_f32_e32 v96, 0x3e000000, v96
	v_pk_mul_f32 v[78:79], v[78:79], v[96:97] op_sel_hi:[1,0]
	v_pk_mul_f32 v[62:63], v[62:63], v[96:97] op_sel_hi:[1,0]
	v_mov_b32_e32 v102, v78
	v_mov_b32_e32 v103, v62
	s_waitcnt vmcnt(3)
	v_pk_mul_f32 v[102:103], v[82:83], v[102:103]
	v_pk_mul_f32 v[80:81], v[80:81], v[96:97] op_sel_hi:[1,0]
	v_pk_mul_f32 v[64:65], v[64:65], v[96:97] op_sel_hi:[1,0]
	v_sub_f32_e32 v97, v102, v103
	v_mov_b32_e32 v102, v62
	v_mov_b32_e32 v103, v78
	v_pk_mul_f32 v[82:83], v[82:83], v[102:103]
	v_mov_b32_e32 v62, v79
	v_mov_b32_e32 v78, v63
	v_add_f32_e32 v102, v83, v82
	v_pk_mul_f32 v[82:83], v[84:85], v[62:63]
	v_pk_mul_f32 v[62:63], v[84:85], v[78:79]
	v_sub_f32_e32 v82, v82, v83
	v_add_f32_e32 v83, v63, v62
	v_mov_b32_e32 v62, v80
	v_mov_b32_e32 v63, v64
	s_waitcnt vmcnt(2)
	v_pk_mul_f32 v[62:63], v[86:87], v[62:63]
	s_nop 0
	v_sub_f32_e32 v84, v62, v63
	v_mov_b32_e32 v62, v64
	v_mov_b32_e32 v63, v80
	v_pk_mul_f32 v[62:63], v[86:87], v[62:63]
	v_mov_b32_e32 v64, v81
	v_add_f32_e32 v85, v63, v62
	v_pk_mul_f32 v[62:63], v[88:89], v[64:65]
	v_mov_b32_e32 v80, v65
	v_sub_f32_e32 v86, v62, v63
	v_pk_mul_f32 v[62:63], v[88:89], v[80:81]
	v_pk_mul_f32 v[64:65], v[56:57], v[76:77]
	v_add_f32_e32 v80, v63, v62
	v_pk_mul_f32 v[62:63], v[54:55], v[74:75]
	v_pk_mul_f32 v[74:75], v[50:51], v[98:99]
	v_pk_mul_f32 v[62:63], v[62:63], v[96:97] op_sel_hi:[1,0]
	v_pk_mul_f32 v[74:75], v[74:75], v[96:97] op_sel_hi:[1,0]
	v_mov_b32_e32 v78, v62
	v_mov_b32_e32 v79, v74
	s_waitcnt vmcnt(1)
	v_pk_mul_f32 v[78:79], v[90:91], v[78:79]
	v_pk_mul_f32 v[76:77], v[52:53], v[100:101]
	v_sub_f32_e32 v81, v78, v79
	v_mov_b32_e32 v78, v74
	v_mov_b32_e32 v79, v62
	v_mov_b32_e32 v62, v75
	v_pk_mul_f32 v[64:65], v[64:65], v[96:97] op_sel_hi:[1,0]
	v_pk_mul_f32 v[76:77], v[76:77], v[96:97] op_sel_hi:[1,0]
	v_pk_mul_f32 v[78:79], v[90:91], v[78:79]
	v_mov_b32_e32 v74, v63
	v_pk_mul_f32 v[62:63], v[92:93], v[62:63]
	v_add_f32_e32 v87, v79, v78
	v_pk_mul_f32 v[78:79], v[92:93], v[74:75]
	v_add_f32_e32 v75, v63, v62
	v_mov_b32_e32 v62, v64
	v_mov_b32_e32 v63, v76
	v_sub_f32_e32 v74, v78, v79
	s_waitcnt vmcnt(0)
	v_pk_mul_f32 v[62:63], v[58:59], v[62:63]
	s_nop 0
	v_sub_f32_e32 v78, v62, v63
	v_mov_b32_e32 v62, v76
	v_mov_b32_e32 v63, v64
	v_pk_mul_f32 v[58:59], v[58:59], v[62:63]
	v_mov_b32_e32 v76, v65
	v_add_f32_e32 v79, v59, v58
	v_pk_mul_f32 v[58:59], v[60:61], v[76:77]
	v_mov_b32_e32 v64, v77
	v_sub_f32_e32 v76, v58, v59
	v_pk_mul_f32 v[58:59], v[60:61], v[64:65]
	s_nop 0
	v_add_f32_e32 v64, v59, v58
	v_lshlrev_b64 v[58:59], 11, v[94:95]
	v_lshl_add_u64 v[58:59], s[44:45], 0, v[58:59]
	v_lshl_add_u64 v[62:63], v[58:59], 0, v[130:131]
	v_cvt_pk_bf16_f32 v58, v97, v82
	v_cvt_pk_bf16_f32 v59, v84, v86
	v_cvt_pk_bf16_f32 v60, v81, v74
	v_cvt_pk_bf16_f32 v61, v78, v76
	v_add_u32_e32 v78, 0x90, v168
	global_store_dwordx4 v[62:63], v[58:61], off
	v_cmp_gt_i32_e32 vcc, s40, v78
	s_nop 0
	v_cvt_pk_bf16_f32 v58, v102, v83
	v_cvt_pk_bf16_f32 v59, v85, v80
	v_cvt_pk_bf16_f32 v60, v87, v75
	v_cvt_pk_bf16_f32 v61, v79, v64
	v_ashrrev_i32_e32 v79, 31, v78
	global_store_dwordx4 v[62:63], v[58:61], off offset:64
	s_nop 1
	v_lshl_add_u64 v[58:59], v[78:79], 2, s[6:7]
	s_nop 0
	v_and_b32_e32 v58, 0xfdf, v78
	v_add_u32_e32 v58, 16, v58
	v_cndmask_b32_e32 v58, v1, v58, vcc
	v_lshlrev_b32_e32 v154, 8, v58
	v_lshl_add_u64 v[80:81], v[156:157], 0, v[154:155]
	global_load_dwordx4 v[58:61], v[80:81], off
	s_waitcnt vmcnt(3)
	v_fmamk_f32 v62, v223, 0x3a800000, v179
	v_rsq_f32_e32 v82, v62
	global_load_dwordx4 v[62:65], v[80:81], off offset:16
	global_load_dwordx4 v[74:77], v[80:81], off offset:32
	v_pk_mul_f32 v[46:47], v[46:47], v[82:83] op_sel_hi:[1,0]
	v_pk_mul_f32 v[42:43], v[42:43], v[82:83] op_sel_hi:[1,0]
	v_pk_mul_f32 v[84:85], v[36:37], v[82:83] op_sel_hi:[1,0]
	v_mov_b32_e32 v36, v47
	v_mov_b32_e32 v37, v43
	v_pk_mul_f32 v[48:49], v[48:49], v[82:83] op_sel_hi:[1,0]
	v_pk_mul_f32 v[44:45], v[44:45], v[82:83] op_sel_hi:[1,0]
	v_pk_mul_f32 v[40:41], v[40:41], v[82:83] op_sel_hi:[1,0]
	v_pk_mul_f32 v[38:39], v[38:39], v[82:83] op_sel_hi:[1,0]
	v_pk_mul_f32 v[82:83], v[34:35], v[82:83] op_sel_hi:[1,0]
	v_mov_b32_e32 v34, v46
	v_mov_b32_e32 v35, v42
	v_pk_mul_f32 v[36:37], v[36:37], v[36:37]
	v_mov_b32_e32 v86, v83
	v_pk_fma_f32 v[34:35], v[34:35], v[34:35], v[36:37]
	v_mov_b32_e32 v36, v48
	v_mov_b32_e32 v37, v44
	v_pk_fma_f32 v[34:35], v[36:37], v[36:37], v[34:35]
	v_mov_b32_e32 v36, v49
	v_mov_b32_e32 v37, v45
	v_mov_b32_e32 v87, v39
	v_pk_fma_f32 v[34:35], v[36:37], v[36:37], v[34:35]
	v_mov_b32_e32 v36, v82
	v_mov_b32_e32 v37, v38
	v_pk_mul_f32 v[86:87], v[86:87], v[86:87]
	v_add_f32_e32 v34, v34, v35
	v_pk_fma_f32 v[36:37], v[36:37], v[36:37], v[86:87]
	v_mov_b32_e32 v86, v84
	v_mov_b32_e32 v87, v40
	v_pk_fma_f32 v[36:37], v[86:87], v[86:87], v[36:37]
	v_mov_b32_e32 v86, v85
	v_mov_b32_e32 v87, v41
	v_pk_fma_f32 v[86:87], v[86:87], v[86:87], v[36:37]
	v_pk_mul_f32 v[46:47], v[70:71], v[46:47]
	v_add_f32_e32 v87, v87, v34
	global_load_dwordx4 v[34:37], v[80:81], off offset:48
	v_add_f32_e32 v80, v86, v87
	ds_bpermute_b32 v81, v182, v80
	v_pk_mul_f32 v[38:39], v[66:67], v[38:39]
	v_pk_mul_f32 v[48:49], v[72:73], v[48:49]
	v_pk_mul_f32 v[40:41], v[68:69], v[40:41]
	s_waitcnt lgkmcnt(0)
	v_add_f32_e32 v80, v80, v81
	ds_bpermute_b32 v81, v132, v80
	s_waitcnt lgkmcnt(0)
	v_add_f32_e32 v80, v80, v81
	v_fmamk_f32 v80, v80, 0x3c800000, v179
	v_rsq_f32_e32 v80, v80
	s_nop 0
	v_mul_f32_e32 v80, 0x3e000000, v80
	v_pk_mul_f32 v[46:47], v[46:47], v[80:81] op_sel_hi:[1,0]
	v_pk_mul_f32 v[38:39], v[38:39], v[80:81] op_sel_hi:[1,0]
	v_mov_b32_e32 v86, v46
	v_mov_b32_e32 v87, v38
	s_waitcnt vmcnt(3)
	v_pk_mul_f32 v[86:87], v[58:59], v[86:87]
	v_pk_mul_f32 v[48:49], v[48:49], v[80:81] op_sel_hi:[1,0]
	v_pk_mul_f32 v[40:41], v[40:41], v[80:81] op_sel_hi:[1,0]
	v_sub_f32_e32 v81, v86, v87
	v_mov_b32_e32 v86, v38
	v_mov_b32_e32 v87, v46
	v_pk_mul_f32 v[58:59], v[58:59], v[86:87]
	v_mov_b32_e32 v38, v47
	v_mov_b32_e32 v46, v39
	v_add_f32_e32 v86, v59, v58
	v_pk_mul_f32 v[58:59], v[60:61], v[38:39]
	v_pk_mul_f32 v[38:39], v[60:61], v[46:47]
	v_sub_f32_e32 v58, v58, v59
	v_add_f32_e32 v59, v39, v38
	v_mov_b32_e32 v38, v48
	v_mov_b32_e32 v39, v40
	s_waitcnt vmcnt(2)
	v_pk_mul_f32 v[38:39], v[62:63], v[38:39]
	s_nop 0
	v_sub_f32_e32 v60, v38, v39
	v_mov_b32_e32 v38, v40
	v_mov_b32_e32 v39, v48
	v_pk_mul_f32 v[38:39], v[62:63], v[38:39]
	v_mov_b32_e32 v40, v49
	v_add_f32_e32 v61, v39, v38
	v_pk_mul_f32 v[38:39], v[64:65], v[40:41]
	v_mov_b32_e32 v48, v41
	v_sub_f32_e32 v62, v38, v39
	v_pk_mul_f32 v[38:39], v[64:65], v[48:49]
	v_pk_mul_f32 v[40:41], v[56:57], v[44:45]
	v_add_f32_e32 v48, v39, v38
	v_pk_mul_f32 v[38:39], v[54:55], v[42:43]
	v_pk_mul_f32 v[42:43], v[50:51], v[82:83]
	v_pk_mul_f32 v[38:39], v[38:39], v[80:81] op_sel_hi:[1,0]
	v_pk_mul_f32 v[42:43], v[42:43], v[80:81] op_sel_hi:[1,0]
	v_mov_b32_e32 v46, v38
	v_mov_b32_e32 v47, v42
	s_waitcnt vmcnt(1)
	v_pk_mul_f32 v[46:47], v[74:75], v[46:47]
	v_pk_mul_f32 v[44:45], v[52:53], v[84:85]
	v_sub_f32_e32 v49, v46, v47
	v_mov_b32_e32 v46, v42
	v_mov_b32_e32 v47, v38
	v_mov_b32_e32 v38, v43
	v_pk_mul_f32 v[40:41], v[40:41], v[80:81] op_sel_hi:[1,0]
	v_pk_mul_f32 v[44:45], v[44:45], v[80:81] op_sel_hi:[1,0]
	v_pk_mul_f32 v[46:47], v[74:75], v[46:47]
	v_mov_b32_e32 v42, v39
	v_pk_mul_f32 v[38:39], v[76:77], v[38:39]
	v_add_f32_e32 v63, v47, v46
	v_pk_mul_f32 v[46:47], v[76:77], v[42:43]
	v_add_f32_e32 v43, v39, v38
	v_mov_b32_e32 v38, v40
	v_mov_b32_e32 v39, v44
	v_sub_f32_e32 v42, v46, v47
	s_waitcnt vmcnt(0)
	v_pk_mul_f32 v[38:39], v[34:35], v[38:39]
	s_nop 0
	v_sub_f32_e32 v46, v38, v39
	v_mov_b32_e32 v38, v44
	v_mov_b32_e32 v39, v40
	v_pk_mul_f32 v[34:35], v[34:35], v[38:39]
	v_mov_b32_e32 v44, v41
	v_add_f32_e32 v47, v35, v34
	v_pk_mul_f32 v[34:35], v[36:37], v[44:45]
	v_mov_b32_e32 v40, v45
	v_sub_f32_e32 v44, v34, v35
	v_pk_mul_f32 v[34:35], v[36:37], v[40:41]
	s_nop 0
	v_add_f32_e32 v40, v35, v34
	v_lshlrev_b64 v[34:35], 11, v[78:79]
	v_lshl_add_u64 v[34:35], s[44:45], 0, v[34:35]
	v_lshl_add_u64 v[38:39], v[34:35], 0, v[130:131]
	v_cvt_pk_bf16_f32 v34, v81, v58
	v_cvt_pk_bf16_f32 v35, v60, v62
	v_cvt_pk_bf16_f32 v36, v49, v42
	v_cvt_pk_bf16_f32 v37, v46, v44
	v_add_u32_e32 v46, 0xa0, v168
	global_store_dwordx4 v[38:39], v[34:37], off
	v_cmp_gt_i32_e32 vcc, s40, v46
	s_nop 0
	v_cvt_pk_bf16_f32 v34, v86, v59
	v_cvt_pk_bf16_f32 v35, v61, v48
	v_cvt_pk_bf16_f32 v36, v63, v43
	v_cvt_pk_bf16_f32 v37, v47, v40
	v_ashrrev_i32_e32 v47, 31, v46
	global_store_dwordx4 v[38:39], v[34:37], off offset:64
	s_nop 1
	v_lshl_add_u64 v[34:35], v[46:47], 2, s[6:7]
	s_nop 0
	v_and_or_b32 v34, v46, s53, 16
	v_cndmask_b32_e32 v34, v1, v34, vcc
	v_lshlrev_b32_e32 v154, 8, v34
	v_lshl_add_u64 v[48:49], v[156:157], 0, v[154:155]
	global_load_dwordx4 v[34:37], v[48:49], off
	s_waitcnt vmcnt(3)
	v_fmamk_f32 v38, v224, 0x3a800000, v179
	v_rsq_f32_e32 v58, v38
	global_load_dwordx4 v[38:41], v[48:49], off offset:16
	global_load_dwordx4 v[42:45], v[48:49], off offset:32
	v_pk_mul_f32 v[30:31], v[30:31], v[58:59] op_sel_hi:[1,0]
	v_pk_mul_f32 v[26:27], v[26:27], v[58:59] op_sel_hi:[1,0]
	v_pk_mul_f32 v[60:61], v[20:21], v[58:59] op_sel_hi:[1,0]
	v_mov_b32_e32 v20, v31
	v_mov_b32_e32 v21, v27
	v_pk_mul_f32 v[32:33], v[32:33], v[58:59] op_sel_hi:[1,0]
	v_pk_mul_f32 v[28:29], v[28:29], v[58:59] op_sel_hi:[1,0]
	v_pk_mul_f32 v[24:25], v[24:25], v[58:59] op_sel_hi:[1,0]
	v_pk_mul_f32 v[22:23], v[22:23], v[58:59] op_sel_hi:[1,0]
	v_pk_mul_f32 v[58:59], v[18:19], v[58:59] op_sel_hi:[1,0]
	v_mov_b32_e32 v18, v30
	v_mov_b32_e32 v19, v26
	v_pk_mul_f32 v[20:21], v[20:21], v[20:21]
	v_mov_b32_e32 v62, v59
	v_pk_fma_f32 v[18:19], v[18:19], v[18:19], v[20:21]
	v_mov_b32_e32 v20, v32
	v_mov_b32_e32 v21, v28
	v_pk_fma_f32 v[18:19], v[20:21], v[20:21], v[18:19]
	v_mov_b32_e32 v20, v33
	v_mov_b32_e32 v21, v29
	v_mov_b32_e32 v63, v23
	v_pk_fma_f32 v[18:19], v[20:21], v[20:21], v[18:19]
	v_mov_b32_e32 v20, v58
	v_mov_b32_e32 v21, v22
	v_pk_mul_f32 v[62:63], v[62:63], v[62:63]
	v_add_f32_e32 v18, v18, v19
	v_pk_fma_f32 v[20:21], v[20:21], v[20:21], v[62:63]
	v_mov_b32_e32 v62, v60
	v_mov_b32_e32 v63, v24
	v_pk_fma_f32 v[20:21], v[62:63], v[62:63], v[20:21]
	v_mov_b32_e32 v62, v61
	v_mov_b32_e32 v63, v25
	v_pk_fma_f32 v[62:63], v[62:63], v[62:63], v[20:21]
	v_pk_mul_f32 v[30:31], v[70:71], v[30:31]
	v_add_f32_e32 v63, v63, v18
	global_load_dwordx4 v[18:21], v[48:49], off offset:48
	v_add_f32_e32 v48, v62, v63
	ds_bpermute_b32 v49, v182, v48
	v_pk_mul_f32 v[22:23], v[66:67], v[22:23]
	v_pk_mul_f32 v[32:33], v[72:73], v[32:33]
	v_pk_mul_f32 v[24:25], v[68:69], v[24:25]
	s_waitcnt lgkmcnt(0)
	v_add_f32_e32 v48, v48, v49
	ds_bpermute_b32 v49, v132, v48
	s_waitcnt lgkmcnt(0)
	v_add_f32_e32 v48, v48, v49
	v_fmamk_f32 v48, v48, 0x3c800000, v179
	v_rsq_f32_e32 v48, v48
	s_nop 0
	v_mul_f32_e32 v48, 0x3e000000, v48
	v_pk_mul_f32 v[30:31], v[30:31], v[48:49] op_sel_hi:[1,0]
	v_pk_mul_f32 v[22:23], v[22:23], v[48:49] op_sel_hi:[1,0]
	v_mov_b32_e32 v62, v30
	v_mov_b32_e32 v63, v22
	s_waitcnt vmcnt(3)
	v_pk_mul_f32 v[62:63], v[34:35], v[62:63]
	v_pk_mul_f32 v[32:33], v[32:33], v[48:49] op_sel_hi:[1,0]
	v_pk_mul_f32 v[24:25], v[24:25], v[48:49] op_sel_hi:[1,0]
	v_sub_f32_e32 v49, v62, v63
	v_mov_b32_e32 v62, v22
	v_mov_b32_e32 v63, v30
	v_pk_mul_f32 v[34:35], v[34:35], v[62:63]
	v_mov_b32_e32 v22, v31
	v_mov_b32_e32 v30, v23
	v_add_f32_e32 v62, v35, v34
	v_pk_mul_f32 v[34:35], v[36:37], v[22:23]
	v_pk_mul_f32 v[22:23], v[36:37], v[30:31]
	v_sub_f32_e32 v34, v34, v35
	v_add_f32_e32 v35, v23, v22
	v_mov_b32_e32 v22, v32
	v_mov_b32_e32 v23, v24
	s_waitcnt vmcnt(2)
	v_pk_mul_f32 v[22:23], v[38:39], v[22:23]
	s_nop 0
	v_sub_f32_e32 v36, v22, v23
	v_mov_b32_e32 v22, v24
	v_mov_b32_e32 v23, v32
	v_pk_mul_f32 v[22:23], v[38:39], v[22:23]
	v_mov_b32_e32 v24, v33
	v_add_f32_e32 v37, v23, v22
	v_pk_mul_f32 v[22:23], v[40:41], v[24:25]
	v_mov_b32_e32 v32, v25
	v_sub_f32_e32 v38, v22, v23
	v_pk_mul_f32 v[22:23], v[40:41], v[32:33]
	v_pk_mul_f32 v[24:25], v[56:57], v[28:29]
	v_add_f32_e32 v32, v23, v22
	v_pk_mul_f32 v[22:23], v[54:55], v[26:27]
	v_pk_mul_f32 v[26:27], v[50:51], v[58:59]
	v_pk_mul_f32 v[22:23], v[22:23], v[48:49] op_sel_hi:[1,0]
	v_pk_mul_f32 v[26:27], v[26:27], v[48:49] op_sel_hi:[1,0]
	v_mov_b32_e32 v30, v22
	v_mov_b32_e32 v31, v26
	s_waitcnt vmcnt(1)
	v_pk_mul_f32 v[30:31], v[42:43], v[30:31]
	v_pk_mul_f32 v[28:29], v[52:53], v[60:61]
	v_sub_f32_e32 v33, v30, v31
	v_mov_b32_e32 v30, v26
	v_mov_b32_e32 v31, v22
	v_mov_b32_e32 v22, v27
	v_pk_mul_f32 v[24:25], v[24:25], v[48:49] op_sel_hi:[1,0]
	v_pk_mul_f32 v[28:29], v[28:29], v[48:49] op_sel_hi:[1,0]
	v_pk_mul_f32 v[30:31], v[42:43], v[30:31]
	v_mov_b32_e32 v26, v23
	v_pk_mul_f32 v[22:23], v[44:45], v[22:23]
	v_add_f32_e32 v39, v31, v30
	v_pk_mul_f32 v[30:31], v[44:45], v[26:27]
	v_add_f32_e32 v27, v23, v22
	v_mov_b32_e32 v22, v24
	v_mov_b32_e32 v23, v28
	v_sub_f32_e32 v26, v30, v31
	s_waitcnt vmcnt(0)
	v_pk_mul_f32 v[22:23], v[18:19], v[22:23]
	s_nop 0
	v_sub_f32_e32 v30, v22, v23
	v_mov_b32_e32 v22, v28
	v_mov_b32_e32 v23, v24
	v_pk_mul_f32 v[18:19], v[18:19], v[22:23]
	v_mov_b32_e32 v28, v25
	v_add_f32_e32 v31, v19, v18
	v_pk_mul_f32 v[18:19], v[20:21], v[28:29]
	v_mov_b32_e32 v24, v29
	v_sub_f32_e32 v28, v18, v19
	v_pk_mul_f32 v[18:19], v[20:21], v[24:25]
	s_nop 0
	v_add_f32_e32 v24, v19, v18
	v_lshlrev_b64 v[18:19], 11, v[46:47]
	v_lshl_add_u64 v[18:19], s[44:45], 0, v[18:19]
	v_lshl_add_u64 v[22:23], v[18:19], 0, v[130:131]
	v_cvt_pk_bf16_f32 v18, v49, v34
	v_cvt_pk_bf16_f32 v19, v36, v38
	v_cvt_pk_bf16_f32 v20, v33, v26
	v_cvt_pk_bf16_f32 v21, v30, v28
	v_add_u32_e32 v30, 0xb0, v168
	global_store_dwordx4 v[22:23], v[18:21], off
	v_cmp_gt_i32_e32 vcc, s40, v30
	s_nop 0
	v_cvt_pk_bf16_f32 v18, v62, v35
	v_cvt_pk_bf16_f32 v19, v37, v32
	v_cvt_pk_bf16_f32 v20, v39, v27
	v_cvt_pk_bf16_f32 v21, v31, v24
	v_ashrrev_i32_e32 v31, 31, v30
	global_store_dwordx4 v[22:23], v[18:21], off offset:64
	s_nop 1
	v_lshl_add_u64 v[18:19], v[30:31], 2, s[6:7]
	s_nop 0
	v_and_b32_e32 v18, 0xfff, v30
	v_add_u32_e32 v18, 16, v18
	v_cndmask_b32_e32 v18, v1, v18, vcc
	v_lshlrev_b32_e32 v154, 8, v18
	v_lshl_add_u64 v[32:33], v[156:157], 0, v[154:155]
	global_load_dwordx4 v[18:21], v[32:33], off
	s_andn2_b64 vcc, exec, s[2:3]
	s_mov_b64 s[2:3], -1
	s_waitcnt vmcnt(3)
	v_fmamk_f32 v22, v225, 0x3a800000, v179
	v_rsq_f32_e32 v34, v22
	global_load_dwordx4 v[22:25], v[32:33], off offset:16
	global_load_dwordx4 v[26:29], v[32:33], off offset:32
	v_pk_mul_f32 v[14:15], v[14:15], v[34:35] op_sel_hi:[1,0]
	v_pk_mul_f32 v[10:11], v[10:11], v[34:35] op_sel_hi:[1,0]
	v_pk_mul_f32 v[36:37], v[4:5], v[34:35] op_sel_hi:[1,0]
	v_mov_b32_e32 v4, v15
	v_mov_b32_e32 v5, v11
	v_pk_mul_f32 v[16:17], v[16:17], v[34:35] op_sel_hi:[1,0]
	v_pk_mul_f32 v[12:13], v[12:13], v[34:35] op_sel_hi:[1,0]
	v_pk_mul_f32 v[8:9], v[8:9], v[34:35] op_sel_hi:[1,0]
	v_pk_mul_f32 v[6:7], v[6:7], v[34:35] op_sel_hi:[1,0]
	v_pk_mul_f32 v[34:35], v[2:3], v[34:35] op_sel_hi:[1,0]
	v_mov_b32_e32 v2, v14
	v_mov_b32_e32 v3, v10
	v_pk_mul_f32 v[4:5], v[4:5], v[4:5]
	v_mov_b32_e32 v38, v35
	v_pk_fma_f32 v[2:3], v[2:3], v[2:3], v[4:5]
	v_mov_b32_e32 v4, v16
	v_mov_b32_e32 v5, v12
	v_pk_fma_f32 v[2:3], v[4:5], v[4:5], v[2:3]
	v_mov_b32_e32 v4, v17
	v_mov_b32_e32 v5, v13
	v_mov_b32_e32 v39, v7
	v_pk_fma_f32 v[2:3], v[4:5], v[4:5], v[2:3]
	v_mov_b32_e32 v4, v34
	v_mov_b32_e32 v5, v6
	v_pk_mul_f32 v[38:39], v[38:39], v[38:39]
	v_add_f32_e32 v2, v2, v3
	v_pk_fma_f32 v[4:5], v[4:5], v[4:5], v[38:39]
	v_mov_b32_e32 v38, v36
	v_mov_b32_e32 v39, v8
	v_pk_fma_f32 v[4:5], v[38:39], v[38:39], v[4:5]
	v_mov_b32_e32 v38, v37
	v_mov_b32_e32 v39, v9
	v_pk_fma_f32 v[38:39], v[38:39], v[38:39], v[4:5]
	v_pk_mul_f32 v[14:15], v[70:71], v[14:15]
	v_add_f32_e32 v39, v39, v2
	global_load_dwordx4 v[2:5], v[32:33], off offset:48
	v_add_f32_e32 v32, v38, v39
	ds_bpermute_b32 v33, v182, v32
	v_pk_mul_f32 v[6:7], v[66:67], v[6:7]
	v_pk_mul_f32 v[16:17], v[72:73], v[16:17]
	v_pk_mul_f32 v[8:9], v[68:69], v[8:9]
	s_waitcnt lgkmcnt(0)
	v_add_f32_e32 v32, v32, v33
	ds_bpermute_b32 v33, v132, v32
	s_waitcnt lgkmcnt(0)
	v_add_f32_e32 v32, v32, v33
	v_fmamk_f32 v32, v32, 0x3c800000, v179
	v_rsq_f32_e32 v32, v32
	s_nop 0
	v_mul_f32_e32 v32, 0x3e000000, v32
	v_pk_mul_f32 v[14:15], v[14:15], v[32:33] op_sel_hi:[1,0]
	v_pk_mul_f32 v[6:7], v[6:7], v[32:33] op_sel_hi:[1,0]
	v_mov_b32_e32 v38, v14
	v_mov_b32_e32 v39, v6
	s_waitcnt vmcnt(3)
	v_pk_mul_f32 v[38:39], v[18:19], v[38:39]
	v_pk_mul_f32 v[16:17], v[16:17], v[32:33] op_sel_hi:[1,0]
	v_pk_mul_f32 v[8:9], v[8:9], v[32:33] op_sel_hi:[1,0]
	v_sub_f32_e32 v33, v38, v39
	v_mov_b32_e32 v38, v6
	v_mov_b32_e32 v39, v14
	v_pk_mul_f32 v[18:19], v[18:19], v[38:39]
	v_mov_b32_e32 v6, v15
	v_mov_b32_e32 v14, v7
	v_add_f32_e32 v38, v19, v18
	v_pk_mul_f32 v[18:19], v[20:21], v[6:7]
	v_pk_mul_f32 v[6:7], v[20:21], v[14:15]
	v_sub_f32_e32 v18, v18, v19
	v_add_f32_e32 v19, v7, v6
	v_mov_b32_e32 v6, v16
	v_mov_b32_e32 v7, v8
	s_waitcnt vmcnt(2)
	v_pk_mul_f32 v[6:7], v[22:23], v[6:7]
	s_nop 0
	v_sub_f32_e32 v20, v6, v7
	v_mov_b32_e32 v6, v8
	v_mov_b32_e32 v7, v16
	v_pk_mul_f32 v[6:7], v[22:23], v[6:7]
	v_mov_b32_e32 v8, v17
	v_add_f32_e32 v21, v7, v6
	v_pk_mul_f32 v[6:7], v[24:25], v[8:9]
	v_mov_b32_e32 v16, v9
	v_sub_f32_e32 v22, v6, v7
	v_pk_mul_f32 v[6:7], v[24:25], v[16:17]
	v_pk_mul_f32 v[8:9], v[56:57], v[12:13]
	v_add_f32_e32 v16, v7, v6
	v_pk_mul_f32 v[6:7], v[54:55], v[10:11]
	v_pk_mul_f32 v[10:11], v[50:51], v[34:35]
	v_pk_mul_f32 v[6:7], v[6:7], v[32:33] op_sel_hi:[1,0]
	v_pk_mul_f32 v[10:11], v[10:11], v[32:33] op_sel_hi:[1,0]
	v_mov_b32_e32 v14, v6
	v_mov_b32_e32 v15, v10
	s_waitcnt vmcnt(1)
	v_pk_mul_f32 v[14:15], v[26:27], v[14:15]
	v_pk_mul_f32 v[12:13], v[52:53], v[36:37]
	v_sub_f32_e32 v17, v14, v15
	v_mov_b32_e32 v14, v10
	v_mov_b32_e32 v15, v6
	v_mov_b32_e32 v6, v11
	v_pk_mul_f32 v[8:9], v[8:9], v[32:33] op_sel_hi:[1,0]
	v_pk_mul_f32 v[12:13], v[12:13], v[32:33] op_sel_hi:[1,0]
	v_pk_mul_f32 v[14:15], v[26:27], v[14:15]
	v_mov_b32_e32 v10, v7
	v_pk_mul_f32 v[6:7], v[28:29], v[6:7]
	v_add_f32_e32 v23, v15, v14
	v_pk_mul_f32 v[14:15], v[28:29], v[10:11]
	v_add_f32_e32 v11, v7, v6
	v_mov_b32_e32 v6, v8
	v_mov_b32_e32 v7, v12
	v_sub_f32_e32 v10, v14, v15
	s_waitcnt vmcnt(0)
	v_pk_mul_f32 v[6:7], v[2:3], v[6:7]
	s_nop 0
	v_sub_f32_e32 v14, v6, v7
	v_mov_b32_e32 v6, v12
	v_mov_b32_e32 v7, v8
	v_pk_mul_f32 v[2:3], v[2:3], v[6:7]
	v_mov_b32_e32 v12, v9
	v_add_f32_e32 v15, v3, v2
	v_pk_mul_f32 v[2:3], v[4:5], v[12:13]
	v_mov_b32_e32 v8, v13
	v_sub_f32_e32 v12, v2, v3
	v_pk_mul_f32 v[2:3], v[4:5], v[8:9]
	s_nop 0
	v_add_f32_e32 v8, v3, v2
	v_lshlrev_b64 v[2:3], 11, v[30:31]
	v_lshl_add_u64 v[2:3], s[44:45], 0, v[2:3]
	v_lshl_add_u64 v[6:7], v[2:3], 0, v[130:131]
	v_cvt_pk_bf16_f32 v2, v33, v18
	v_cvt_pk_bf16_f32 v3, v20, v22
	v_cvt_pk_bf16_f32 v4, v17, v10
	v_cvt_pk_bf16_f32 v5, v14, v12
	global_store_dwordx4 v[6:7], v[2:5], off
	s_nop 1
	v_cvt_pk_bf16_f32 v2, v38, v19
	v_cvt_pk_bf16_f32 v3, v21, v16
	v_cvt_pk_bf16_f32 v4, v23, v11
	v_cvt_pk_bf16_f32 v5, v15, v8
	global_store_dwordx4 v[6:7], v[2:5], off offset:64
	s_cbranch_vccnz .LBB0_1563
	s_andn2_b64 vcc, exec, s[4:5]
	s_cbranch_vccnz .LBB0_1562
	s_barrier
	s_branch .LBB0_1562
